# write-through (sc1 nt) on the LayerNorm phases' full-row 16-byte f32 stores (X1 / out) so the grid barrier's L2 write-back and kernel-end flush find fewer dirty lines
# speedup vs baseline: 1.0135x; 1.0042x over previous
.LBB0_359:
	v_add_f32_e32 v130, v126, v127
	v_add_f32_e32 v131, v128, v129
	v_add_f32_e32 v130, v130, v131
	v_and_b32_e32 v131, 64, v243
	v_add_u32_e32 v131, 64, v131
	v_xor_b32_e32 v132, 1, v243
	v_cmp_lt_i32_e32 vcc, v132, v131
	v_add_f32_e32 v130, v244, v130
	v_lshlrev_b32_e32 v192, 4, v1
	v_cndmask_b32_e32 v132, v243, v132, vcc
	v_lshlrev_b32_e32 v202, 2, v132
	ds_bpermute_b32 v132, v202, v130
	s_and_b32 s2, s69, 0xffff8000
	s_add_i32 s2, s2, 0x8000
	s_waitcnt lgkmcnt(0)
	v_add_f32_e32 v130, v130, v132
	v_xor_b32_e32 v132, 2, v243
	v_cmp_lt_i32_e32 vcc, v132, v131
	s_nop 1
	v_cndmask_b32_e32 v132, v243, v132, vcc
	v_lshlrev_b32_e32 v203, 2, v132
	ds_bpermute_b32 v132, v203, v130
	s_waitcnt lgkmcnt(0)
	v_add_f32_e32 v130, v130, v132
	v_xor_b32_e32 v132, 4, v243
	v_cmp_lt_i32_e32 vcc, v132, v131
	s_nop 1
	v_cndmask_b32_e32 v132, v243, v132, vcc
	v_lshlrev_b32_e32 v204, 2, v132
	ds_bpermute_b32 v132, v204, v130
	s_waitcnt lgkmcnt(0)
	v_add_f32_e32 v130, v130, v132
	v_xor_b32_e32 v132, 8, v243
	v_cmp_lt_i32_e32 vcc, v132, v131
	s_nop 1
	v_cndmask_b32_e32 v132, v243, v132, vcc
	v_lshlrev_b32_e32 v205, 2, v132
	ds_bpermute_b32 v132, v205, v130
	s_waitcnt lgkmcnt(0)
	v_add_f32_e32 v130, v130, v132
	v_xor_b32_e32 v132, 16, v243
	v_cmp_lt_i32_e32 vcc, v132, v131
	s_nop 1
	v_cndmask_b32_e32 v132, v243, v132, vcc
	v_lshlrev_b32_e32 v206, 2, v132
	ds_bpermute_b32 v132, v206, v130
	s_waitcnt lgkmcnt(0)
	v_add_f32_e32 v130, v130, v132
	v_xor_b32_e32 v132, 32, v243
	v_cmp_lt_i32_e32 vcc, v132, v131
	s_nop 1
	v_cndmask_b32_e32 v131, v243, v132, vcc
	v_lshlrev_b32_e32 v207, 2, v131
	ds_bpermute_b32 v131, v207, v130
	s_waitcnt lgkmcnt(0)
	v_add_f32_e32 v144, v130, v131
	v_fmamk_f32 v143, v144, 0xb9800000, v87
	v_fmamk_f32 v142, v144, 0xb9800000, v86
	v_fmamk_f32 v89, v144, 0xb9800000, v89
	v_fmac_f32_e32 v88, 0xb9800000, v144
	v_pk_mul_f32 v[86:87], v[88:89], v[88:89]
	v_pk_mul_f32 v[130:131], v[142:143], v[142:143]
	v_fmamk_f32 v141, v144, 0xb9800000, v79
	v_pk_mov_b32 v[132:133], v[130:131], v[86:87] op_sel:[1,0]
	v_mov_b32_e32 v131, v87
	v_fmamk_f32 v140, v144, 0xb9800000, v78
	v_fmamk_f32 v81, v144, 0xb9800000, v81
	v_fmac_f32_e32 v80, 0xb9800000, v144
	v_fmamk_f32 v138, v144, 0xb9800000, v74
	v_pk_add_f32 v[86:87], v[132:133], v[130:131]
	v_pk_mul_f32 v[78:79], v[80:81], v[80:81]
	v_pk_mul_f32 v[130:131], v[140:141], v[140:141]
	v_fmamk_f32 v139, v144, 0xb9800000, v75
	v_mul_f32_e32 v74, v138, v138
	v_pk_mov_b32 v[132:133], v[130:131], v[78:79] op_sel:[1,0]
	v_mov_b32_e32 v131, v79
	v_fmac_f32_e32 v76, 0xb9800000, v144
	v_pk_fma_f32 v[74:75], v[138:139], v[138:139], v[74:75] op_sel_hi:[1,1,0]
	v_pk_add_f32 v[78:79], v[132:133], v[130:131]
	v_fmamk_f32 v77, v144, 0xb9800000, v77
	v_mul_f32_e32 v74, v76, v76
	v_pk_add_f32 v[86:87], v[86:87], v[86:87] op_sel_hi:[0,1]
	v_pk_add_f32 v[78:79], v[78:79], v[78:79] op_sel_hi:[0,1]
	v_pk_fma_f32 v[130:131], v[76:77], v[76:77], v[74:75] op_sel_hi:[1,1,0]
	v_fmamk_f32 v137, v144, 0xb9800000, v85
	v_fmamk_f32 v136, v144, 0xb9800000, v84
	v_fmamk_f32 v83, v144, 0xb9800000, v83
	v_fmac_f32_e32 v82, 0xb9800000, v144
	v_mul_f32_e32 v74, v82, v82
	v_mul_f32_e32 v130, v83, v83
	v_mul_f32_e32 v86, v136, v136
	v_mul_f32_e32 v78, v137, v137
	v_pk_add_f32 v[74:75], v[74:75], v[130:131]
	v_pk_add_f32 v[78:79], v[86:87], v[78:79]
	v_fmamk_f32 v135, v144, 0xb9800000, v71
	v_fmamk_f32 v134, v144, 0xb9800000, v70
	v_fmamk_f32 v73, v144, 0xb9800000, v73
	v_fmac_f32_e32 v72, 0xb9800000, v144
	v_fmamk_f32 v132, v144, 0xb9800000, v66
	v_pk_add_f32 v[74:75], v[74:75], v[78:79]
	v_pk_mul_f32 v[70:71], v[72:73], v[72:73]
	v_pk_mul_f32 v[78:79], v[134:135], v[134:135]
	v_fmamk_f32 v133, v144, 0xb9800000, v67
	v_mul_f32_e32 v66, v132, v132
	v_pk_mov_b32 v[84:85], v[78:79], v[70:71] op_sel:[1,0]
	v_mov_b32_e32 v79, v71
	v_fmac_f32_e32 v68, 0xb9800000, v144
	v_pk_fma_f32 v[66:67], v[132:133], v[132:133], v[66:67] op_sel_hi:[1,1,0]
	v_pk_add_f32 v[70:71], v[84:85], v[78:79]
	v_fmamk_f32 v69, v144, 0xb9800000, v69
	v_mul_f32_e32 v66, v68, v68
	v_pk_add_f32 v[74:75], v[74:75], v[74:75] op_sel_hi:[0,1]
	v_pk_add_f32 v[70:71], v[70:71], v[70:71] op_sel_hi:[0,1]
	v_pk_fma_f32 v[78:79], v[68:69], v[68:69], v[66:67] op_sel_hi:[1,1,0]
	v_fmamk_f32 v131, v144, 0xb9800000, v93
	v_fmamk_f32 v130, v144, 0xb9800000, v92
	v_fmamk_f32 v91, v144, 0xb9800000, v91
	v_fmac_f32_e32 v90, 0xb9800000, v144
	v_mul_f32_e32 v66, v90, v90
	v_mul_f32_e32 v78, v91, v91
	v_mul_f32_e32 v70, v130, v130
	v_mul_f32_e32 v74, v131, v131
	v_pk_add_f32 v[66:67], v[66:67], v[78:79]
	v_pk_add_f32 v[70:71], v[70:71], v[74:75]
	v_fmamk_f32 v201, v144, 0xb9800000, v95
	v_pk_add_f32 v[66:67], v[66:67], v[70:71]
	v_fmamk_f32 v200, v144, 0xb9800000, v94
	v_fmamk_f32 v97, v144, 0xb9800000, v97
	v_fmac_f32_e32 v96, 0xb9800000, v144
	v_pk_add_f32 v[66:67], v[66:67], v[66:67] op_sel_hi:[0,1]
	v_pk_mul_f32 v[70:71], v[96:97], v[96:97]
	v_pk_mul_f32 v[74:75], v[200:201], v[200:201]
	v_fmamk_f32 v94, v144, 0xb9800000, v98
	v_pk_mov_b32 v[78:79], v[74:75], v[70:71] op_sel:[1,0]
	v_mov_b32_e32 v75, v71
	v_fmamk_f32 v95, v144, 0xb9800000, v99
	v_fmac_f32_e32 v100, 0xb9800000, v144
	v_mul_f32_e32 v66, v94, v94
	v_pk_add_f32 v[70:71], v[78:79], v[74:75]
	v_fmamk_f32 v101, v144, 0xb9800000, v101
	v_pk_fma_f32 v[74:75], v[94:95], v[94:95], v[66:67] op_sel_hi:[1,1,0]
	v_mul_f32_e32 v66, v100, v100
	v_pk_add_f32 v[70:71], v[70:71], v[70:71] op_sel_hi:[0,1]
	v_pk_fma_f32 v[78:79], v[100:101], v[100:101], v[66:67] op_sel_hi:[1,1,0]
	v_fmamk_f32 v93, v144, 0xb9800000, v113
	v_fmamk_f32 v92, v144, 0xb9800000, v112
	v_fmamk_f32 v111, v144, 0xb9800000, v111
	v_fmac_f32_e32 v110, 0xb9800000, v144
	v_mul_f32_e32 v74, v110, v110
	v_mul_f32_e32 v78, v111, v111
	v_mul_f32_e32 v70, v92, v92
	v_mul_f32_e32 v66, v93, v93
	v_pk_add_f32 v[74:75], v[74:75], v[78:79]
	v_pk_add_f32 v[66:67], v[70:71], v[66:67]
	v_fmamk_f32 v87, v144, 0xb9800000, v107
	v_pk_add_f32 v[66:67], v[74:75], v[66:67]
	v_fmamk_f32 v86, v144, 0xb9800000, v106
	v_fmamk_f32 v109, v144, 0xb9800000, v109
	v_fmac_f32_e32 v108, 0xb9800000, v144
	v_pk_add_f32 v[66:67], v[66:67], v[66:67] op_sel_hi:[0,1]
	v_pk_mul_f32 v[70:71], v[108:109], v[108:109]
	v_pk_mul_f32 v[74:75], v[86:87], v[86:87]
	v_fmamk_f32 v84, v144, 0xb9800000, v102
	v_pk_mov_b32 v[78:79], v[74:75], v[70:71] op_sel:[1,0]
	v_mov_b32_e32 v75, v71
	v_fmamk_f32 v85, v144, 0xb9800000, v103
	v_fmac_f32_e32 v104, 0xb9800000, v144
	v_mul_f32_e32 v66, v84, v84
	v_pk_add_f32 v[70:71], v[78:79], v[74:75]
	v_fmamk_f32 v105, v144, 0xb9800000, v105
	v_pk_fma_f32 v[74:75], v[84:85], v[84:85], v[66:67] op_sel_hi:[1,1,0]
	v_mul_f32_e32 v66, v104, v104
	v_pk_add_f32 v[70:71], v[70:71], v[70:71] op_sel_hi:[0,1]
	v_pk_fma_f32 v[98:99], v[104:105], v[104:105], v[66:67] op_sel_hi:[1,1,0]
	v_fmamk_f32 v79, v144, 0xb9800000, v125
	v_fmamk_f32 v78, v144, 0xb9800000, v124
	v_fmamk_f32 v123, v144, 0xb9800000, v123
	v_fmac_f32_e32 v122, 0xb9800000, v144
	v_mul_f32_e32 v74, v122, v122
	v_mul_f32_e32 v98, v123, v123
	v_mul_f32_e32 v70, v78, v78
	v_mul_f32_e32 v66, v79, v79
	v_pk_add_f32 v[74:75], v[74:75], v[98:99]
	v_pk_add_f32 v[66:67], v[70:71], v[66:67]
	v_fmamk_f32 v117, v144, 0xb9800000, v117
	v_pk_add_f32 v[66:67], v[74:75], v[66:67]
	v_fmamk_f32 v75, v144, 0xb9800000, v115
	v_fmamk_f32 v74, v144, 0xb9800000, v114
	v_fmac_f32_e32 v116, 0xb9800000, v144
	v_pk_add_f32 v[98:99], v[66:67], v[66:67] op_sel_hi:[0,1]
	v_pk_mul_f32 v[66:67], v[116:117], v[116:117]
	v_pk_mul_f32 v[70:71], v[74:75], v[74:75]
	v_fmac_f32_e32 v120, 0xb9800000, v144
	v_pk_mov_b32 v[102:103], v[70:71], v[66:67] op_sel:[1,0]
	v_mov_b32_e32 v71, v67
	v_pk_add_f32 v[66:67], v[102:103], v[70:71]
	v_fmamk_f32 v70, v144, 0xb9800000, v118
	v_pk_add_f32 v[102:103], v[66:67], v[66:67] op_sel_hi:[0,1]
	v_fmamk_f32 v71, v144, 0xb9800000, v119
	v_mul_f32_e32 v66, v70, v70
	v_fmamk_f32 v121, v144, 0xb9800000, v121
	v_pk_fma_f32 v[106:107], v[70:71], v[70:71], v[66:67] op_sel_hi:[1,1,0]
	v_mul_f32_e32 v66, v120, v120
	v_pk_fma_f32 v[112:113], v[120:121], v[120:121], v[66:67] op_sel_hi:[1,1,0]
	v_fmamk_f32 v67, v144, 0xb9800000, v129
	v_fmamk_f32 v66, v144, 0xb9800000, v128
	v_fmamk_f32 v127, v144, 0xb9800000, v127
	v_fmac_f32_e32 v126, 0xb9800000, v144
	v_mul_f32_e32 v106, v126, v126
	v_mul_f32_e32 v112, v127, v127
	v_mul_f32_e32 v102, v66, v66
	v_mul_f32_e32 v98, v67, v67
	v_pk_add_f32 v[106:107], v[106:107], v[112:113]
	v_pk_add_f32 v[98:99], v[102:103], v[98:99]
	ds_read_b128 v[112:115], v241
	ds_read_b128 v[144:147], v241 offset:16384
	v_pk_add_f32 v[98:99], v[106:107], v[98:99]
	ds_read_b128 v[148:151], v241 offset:17408
	ds_read_b128 v[208:211], v241 offset:1024
	v_add_f32_e32 v98, v98, v99
	ds_bpermute_b32 v99, v202, v98
	s_waitcnt lgkmcnt(0)
	v_add_f32_e32 v98, v98, v99
	ds_bpermute_b32 v99, v203, v98
	s_waitcnt lgkmcnt(0)
	v_add_f32_e32 v98, v98, v99
	ds_bpermute_b32 v99, v204, v98
	s_waitcnt lgkmcnt(0)
	v_add_f32_e32 v98, v98, v99
	ds_bpermute_b32 v99, v205, v98
	s_waitcnt lgkmcnt(0)
	v_add_f32_e32 v98, v98, v99
	ds_bpermute_b32 v99, v206, v98
	s_waitcnt lgkmcnt(0)
	v_add_f32_e32 v98, v98, v99
	ds_bpermute_b32 v99, v207, v98
	s_waitcnt lgkmcnt(0)
	v_add_f32_e32 v98, v98, v99
	v_fmamk_f32 v98, v98, 0x39800000, v179
	v_mul_f32_e32 v99, 0x4f800000, v98
	v_cmp_gt_f32_e32 vcc, s79, v98
	s_nop 1
	v_cndmask_b32_e32 v98, v98, v99, vcc
	v_sqrt_f32_e32 v99, v98
	s_nop 0
	v_add_u32_e32 v102, -1, v99
	v_fma_f32 v103, -v102, v99, v98
	v_cmp_ge_f32_e64 s[0:1], 0, v103
	v_add_u32_e32 v103, 1, v99
	s_nop 0
	v_cndmask_b32_e64 v102, v99, v102, s[0:1]
	v_fma_f32 v99, -v103, v99, v98
	v_cmp_lt_f32_e64 s[0:1], 0, v99
	s_nop 1
	v_cndmask_b32_e64 v99, v102, v103, s[0:1]
	v_mul_f32_e32 v102, 0x37800000, v99
	v_cndmask_b32_e32 v99, v99, v102, vcc
	v_cmp_class_f32_e32 vcc, v98, v242
	s_nop 1
	v_cndmask_b32_e32 v98, v99, v98, vcc
	v_div_scale_f32 v99, s[0:1], v98, v98, 1.0
	v_rcp_f32_e32 v102, v99
	s_nop 0
	v_fma_f32 v103, -v99, v102, 1.0
	v_fmac_f32_e32 v102, v103, v102
	v_div_scale_f32 v103, vcc, 1.0, v98, 1.0
	v_mul_f32_e32 v106, v103, v102
	v_fma_f32 v107, -v99, v106, v103
	v_fmac_f32_e32 v106, v107, v102
	v_fma_f32 v99, -v99, v106, v103
	v_div_fmas_f32 v99, v99, v102, v106
	v_div_fixup_f32 v102, v99, v98, 1.0
	v_pk_mul_f32 v[88:89], v[88:89], v[102:103] op_sel_hi:[1,0]
	v_pk_mul_f32 v[106:107], v[142:143], v[102:103] op_sel_hi:[1,0]
	v_pk_fma_f32 v[154:155], v[114:115], v[88:89], v[146:147]
	v_pk_fma_f32 v[152:153], v[112:113], v[106:107], v[144:145]
	v_mov_b32_e32 v107, v155
	v_pk_mov_b32 v[88:89], v[152:153], v[154:155] op_sel:[1,0]
	v_mov_b32_e32 v106, v152
	v_pk_add_f32 v[88:89], v[88:89], v[106:107]
	v_pk_mul_f32 v[80:81], v[80:81], v[102:103] op_sel_hi:[1,0]
	v_pk_mul_f32 v[106:107], v[140:141], v[102:103] op_sel_hi:[1,0]
	v_pk_fma_f32 v[150:151], v[210:211], v[80:81], v[150:151]
	v_pk_fma_f32 v[148:149], v[208:209], v[106:107], v[148:149]
	global_store_dwordx4 v192, v[152:155], s[54:55] sc1 nt
	global_store_dwordx4 v192, v[148:151], s[54:55] offset:1024 sc1 nt
	ds_read_b128 v[112:115], v241 offset:18432
	ds_read_b128 v[140:143], v241 offset:2048
	ds_read_b128 v[208:211], v241 offset:19456
	ds_read_b128 v[212:215], v241 offset:3072
	v_pk_mov_b32 v[80:81], v[148:149], v[150:151] op_sel:[1,0]
	v_mov_b32_e32 v106, v148
	v_mov_b32_e32 v107, v151
	v_pk_add_f32 v[80:81], v[80:81], v[106:107]
	v_pk_mul_f32 v[106:107], v[138:139], v[102:103] op_sel_hi:[1,0]
	v_pk_mul_f32 v[76:77], v[76:77], v[102:103] op_sel_hi:[1,0]
	s_waitcnt lgkmcnt(2)
	v_pk_fma_f32 v[144:145], v[140:141], v[106:107], v[112:113]
	v_pk_mul_f32 v[82:83], v[82:83], v[102:103] op_sel_hi:[1,0]
	v_pk_mul_f32 v[112:113], v[136:137], v[102:103] op_sel_hi:[1,0]
	v_add_f32_e32 v88, v88, v89
	v_pk_add_f32 v[80:81], v[80:81], v[80:81] op_sel_hi:[0,1]
	v_pk_fma_f32 v[146:147], v[142:143], v[76:77], v[114:115]
	s_waitcnt lgkmcnt(0)
	v_pk_fma_f32 v[142:143], v[214:215], v[112:113], v[210:211]
	v_pk_fma_f32 v[140:141], v[212:213], v[82:83], v[208:209]
	v_add_f32_e32 v89, 0, v88
	global_store_dwordx4 v192, v[144:147], s[54:55] offset:2048 sc1 nt
	v_add_f32_e32 v77, v144, v145
	v_add_f32_e32 v107, v146, v147
	global_store_dwordx4 v192, v[140:143], s[54:55] offset:3072 sc1 nt
	v_mov_b32_e32 v76, v140
	v_mov_b32_e32 v106, v141
	v_mov_b32_e32 v80, v142
	v_mov_b32_e32 v88, v143
	v_pk_add_f32 v[76:77], v[76:77], v[106:107]
	v_pk_add_f32 v[80:81], v[80:81], v[88:89]
	v_pk_mul_f32 v[88:89], v[134:135], v[102:103] op_sel_hi:[1,0]
	v_pk_add_f32 v[76:77], v[76:77], v[80:81]
	ds_read_b128 v[80:83], v241 offset:4096
	ds_read_b128 v[112:115], v241 offset:20480
	v_pk_mul_f32 v[72:73], v[72:73], v[102:103] op_sel_hi:[1,0]
	ds_read_b128 v[208:211], v241 offset:21504
	ds_read_b128 v[212:215], v241 offset:5120
	v_lshl_add_u64 v[98:99], s[54:55], 0, v[192:193]
	v_pk_mul_f32 v[68:69], v[68:69], v[102:103] op_sel_hi:[1,0]
	s_waitcnt lgkmcnt(2)
	v_pk_fma_f32 v[138:139], v[82:83], v[72:73], v[114:115]
	v_pk_fma_f32 v[136:137], v[80:81], v[88:89], v[112:113]
	v_add_co_u32_e32 v72, vcc, s77, v98
	v_pk_mov_b32 v[80:81], v[136:137], v[138:139] op_sel:[1,0]
	v_mov_b32_e32 v82, v136
	v_mov_b32_e32 v83, v139
	v_addc_co_u32_e32 v73, vcc, 0, v99, vcc
	v_pk_add_f32 v[80:81], v[80:81], v[82:83]
	v_add_co_u32_e32 v118, vcc, s75, v98
	v_pk_add_f32 v[106:107], v[80:81], v[80:81] op_sel_hi:[0,1]
	v_pk_mul_f32 v[80:81], v[132:133], v[102:103] op_sel_hi:[1,0]
	v_addc_co_u32_e32 v119, vcc, 0, v99, vcc
	s_waitcnt lgkmcnt(0)
	v_pk_fma_f32 v[134:135], v[214:215], v[68:69], v[210:211]
	v_pk_fma_f32 v[132:133], v[212:213], v[80:81], v[208:209]
	global_store_dwordx4 v[118:119], v[136:139], off offset:-4096 sc1 nt
	global_store_dwordx4 v[72:73], v[132:135], off offset:1024 sc1 nt
	ds_read_b128 v[80:83], v241 offset:22528
	ds_read_b128 v[112:115], v241 offset:6144
	v_pk_mul_f32 v[128:129], v[90:91], v[102:103] op_sel_hi:[1,0]
	v_pk_mul_f32 v[130:131], v[130:131], v[102:103] op_sel_hi:[1,0]
	ds_read_b128 v[88:91], v241 offset:23552
	ds_read_b128 v[208:211], v241 offset:7168
	v_pk_add_f32 v[76:77], v[76:77], v[76:77] op_sel_hi:[0,1]
	s_waitcnt lgkmcnt(2)
	v_pk_fma_f32 v[130:131], v[114:115], v[130:131], v[82:83]
	v_pk_fma_f32 v[128:129], v[112:113], v[128:129], v[80:81]
	v_add_f32_e32 v69, v132, v133
	v_add_f32_e32 v125, v134, v135
	v_mov_b32_e32 v68, v128
	v_mov_b32_e32 v124, v129
	v_mov_b32_e32 v106, v130
	v_mov_b32_e32 v76, v131
	v_pk_add_f32 v[68:69], v[68:69], v[124:125]
	v_pk_add_f32 v[76:77], v[106:107], v[76:77]
	v_pk_mul_f32 v[80:81], v[96:97], v[102:103] op_sel_hi:[1,0]
	v_pk_add_f32 v[68:69], v[68:69], v[76:77]
	v_pk_mul_f32 v[76:77], v[200:201], v[102:103] op_sel_hi:[1,0]
	s_waitcnt lgkmcnt(0)
	v_pk_fma_f32 v[114:115], v[210:211], v[80:81], v[90:91]
	v_pk_fma_f32 v[112:113], v[208:209], v[76:77], v[88:89]
	global_store_dwordx4 v[72:73], v[128:131], off offset:2048 sc1 nt
	global_store_dwordx4 v[72:73], v[112:115], off offset:3072 sc1 nt
	ds_read_b128 v[80:83], v241 offset:8192
	ds_read_b128 v[88:91], v241 offset:24576
	ds_read_b128 v[208:211], v241 offset:25600
	ds_read_b128 v[212:215], v241 offset:9216
	v_pk_mov_b32 v[72:73], v[112:113], v[114:115] op_sel:[1,0]
	v_mov_b32_e32 v76, v112
	v_mov_b32_e32 v77, v115
	v_pk_add_f32 v[72:73], v[72:73], v[76:77]
	v_pk_mul_f32 v[76:77], v[94:95], v[102:103] op_sel_hi:[1,0]
	v_pk_mul_f32 v[94:95], v[100:101], v[102:103] op_sel_hi:[1,0]
	v_pk_add_f32 v[68:69], v[68:69], v[68:69] op_sel_hi:[0,1]
	s_waitcnt lgkmcnt(2)
	v_pk_fma_f32 v[96:97], v[82:83], v[94:95], v[90:91]
	v_pk_fma_f32 v[94:95], v[80:81], v[76:77], v[88:89]
	v_pk_mul_f32 v[82:83], v[110:111], v[102:103] op_sel_hi:[1,0]
	v_pk_mul_f32 v[88:89], v[92:93], v[102:103] op_sel_hi:[1,0]
	s_waitcnt lgkmcnt(0)
	v_pk_fma_f32 v[90:91], v[212:213], v[82:83], v[208:209]
	v_pk_fma_f32 v[92:93], v[214:215], v[88:89], v[210:211]
	global_store_dwordx4 v[118:119], v[94:97], off sc1 nt
	v_add_f32_e32 v77, v94, v95
	v_add_f32_e32 v81, v96, v97
	global_store_dwordx4 v[118:119], v[90:93], off offset:1024 sc1 nt
	v_mov_b32_e32 v76, v90
	v_mov_b32_e32 v80, v91
	v_pk_add_f32 v[72:73], v[72:73], v[72:73] op_sel_hi:[0,1]
	v_pk_add_f32 v[76:77], v[76:77], v[80:81]
	ds_read_b128 v[80:83], v241 offset:26624
	ds_read_b128 v[208:211], v241 offset:10240
	v_mov_b32_e32 v72, v92
	v_mov_b32_e32 v68, v93
	v_pk_add_f32 v[68:69], v[72:73], v[68:69]
	v_pk_mul_f32 v[72:73], v[86:87], v[102:103] op_sel_hi:[1,0]
	v_pk_add_f32 v[68:69], v[76:77], v[68:69]
	v_pk_mul_f32 v[76:77], v[108:109], v[102:103] op_sel_hi:[1,0]
	ds_read_b128 v[106:109], v241 offset:27648
	ds_read_b128 v[212:215], v241 offset:11264
	s_waitcnt lgkmcnt(2)
	v_pk_fma_f32 v[88:89], v[76:77], v[210:211], v[82:83]
	v_pk_fma_f32 v[86:87], v[72:73], v[208:209], v[80:81]
	v_mov_b32_e32 v77, v89
	v_pk_mov_b32 v[72:73], v[86:87], v[88:89] op_sel:[1,0]
	v_mov_b32_e32 v76, v86
	v_pk_add_f32 v[72:73], v[72:73], v[76:77]
	v_pk_mul_f32 v[76:77], v[84:85], v[102:103] op_sel_hi:[1,0]
	v_pk_mul_f32 v[80:81], v[104:105], v[102:103] op_sel_hi:[1,0]
	s_waitcnt lgkmcnt(0)
	v_pk_fma_f32 v[82:83], v[76:77], v[212:213], v[106:107]
	v_pk_fma_f32 v[84:85], v[80:81], v[214:215], v[108:109]
	global_store_dwordx4 v[118:119], v[86:89], off offset:2048 sc1 nt
	global_store_dwordx4 v[118:119], v[82:85], off offset:3072 sc1 nt
	ds_read_b128 v[104:107], v241 offset:12288
	ds_read_b128 v[108:111], v241 offset:28672
	v_pk_mul_f32 v[118:119], v[122:123], v[102:103] op_sel_hi:[1,0]
	v_pk_mul_f32 v[78:79], v[78:79], v[102:103] op_sel_hi:[1,0]
	v_pk_add_f32 v[68:69], v[68:69], v[68:69] op_sel_hi:[0,1]
	v_pk_add_f32 v[72:73], v[72:73], v[72:73] op_sel_hi:[0,1]
	ds_read_b128 v[122:125], v241 offset:29696
	ds_read_b128 v[208:211], v241 offset:13312
	s_waitcnt lgkmcnt(2)
	v_pk_fma_f32 v[80:81], v[78:79], v[106:107], v[110:111]
	v_pk_fma_f32 v[78:79], v[118:119], v[104:105], v[108:109]
	v_add_f32_e32 v77, v82, v83
	v_add_f32_e32 v101, v84, v85
	v_mov_b32_e32 v76, v78
	v_mov_b32_e32 v100, v79
	v_mov_b32_e32 v72, v80
	v_mov_b32_e32 v68, v81
	v_pk_add_f32 v[76:77], v[76:77], v[100:101]
	v_pk_add_f32 v[68:69], v[72:73], v[68:69]
	v_pk_mul_f32 v[72:73], v[116:117], v[102:103] op_sel_hi:[1,0]
	v_pk_add_f32 v[68:69], v[76:77], v[68:69]
	s_waitcnt lgkmcnt(0)
	v_pk_fma_f32 v[76:77], v[72:73], v[210:211], v[124:125]
	v_pk_add_f32 v[100:101], v[68:69], v[68:69] op_sel:[0,1] op_sel_hi:[1,0]
	v_pk_mul_f32 v[68:69], v[74:75], v[102:103] op_sel_hi:[1,0]
	v_mov_b32_e32 v73, v77
	v_pk_fma_f32 v[74:75], v[68:69], v[208:209], v[122:123]
	ds_read_b128 v[104:107], v241 offset:30720
	ds_read_b128 v[108:111], v241 offset:14336
	v_pk_mov_b32 v[68:69], v[74:75], v[76:77] op_sel:[1,0]
	v_mov_b32_e32 v72, v74
	v_pk_add_f32 v[68:69], v[68:69], v[72:73]
	v_pk_mul_f32 v[66:67], v[66:67], v[102:103] op_sel_hi:[1,0]
	v_pk_add_f32 v[124:125], v[68:69], v[68:69] op_sel:[0,1] op_sel_hi:[1,0]
	v_pk_mul_f32 v[68:69], v[70:71], v[102:103] op_sel_hi:[1,0]
	v_pk_mul_f32 v[70:71], v[120:121], v[102:103] op_sel_hi:[1,0]
	ds_read_b128 v[116:119], v241 offset:31744
	ds_read_b128 v[120:123], v241 offset:15360
	s_waitcnt lgkmcnt(2)
	v_pk_fma_f32 v[72:73], v[70:71], v[110:111], v[106:107]
	v_pk_fma_f32 v[70:71], v[68:69], v[108:109], v[104:105]
	v_pk_mul_f32 v[108:109], v[126:127], v[102:103] op_sel_hi:[1,0]
	v_add_f32_e32 v104, v70, v71
	s_waitcnt lgkmcnt(0)
	v_pk_fma_f32 v[68:69], v[66:67], v[122:123], v[118:119]
	v_pk_fma_f32 v[66:67], v[108:109], v[120:121], v[116:117]
	v_add_f32_e32 v106, v72, v73
	v_mov_b32_e32 v125, v66
	v_mov_b32_e32 v101, v67
	v_mov_b32_e32 v105, v68
	v_mov_b32_e32 v107, v69
	v_pk_add_f32 v[100:101], v[124:125], v[100:101]
	v_pk_add_f32 v[102:103], v[104:105], v[106:107]
	v_add_co_u32_e32 v98, vcc, s78, v98
	v_pk_add_f32 v[100:101], v[100:101], v[102:103]
	s_nop 0
	v_addc_co_u32_e32 v99, vcc, 0, v99, vcc
	v_add_f32_e32 v100, v100, v101
	ds_bpermute_b32 v101, v202, v100
	global_store_dwordx4 v[98:99], v[78:81], off sc1 nt
	global_store_dwordx4 v[98:99], v[74:77], off offset:1024 sc1 nt
	global_store_dwordx4 v[98:99], v[70:73], off offset:2048 sc1 nt
	global_store_dwordx4 v[98:99], v[66:69], off offset:3072 sc1 nt
	s_waitcnt lgkmcnt(0)
	v_add_f32_e32 v100, v100, v101
	ds_bpermute_b32 v101, v203, v100
	s_waitcnt lgkmcnt(0)
	v_add_f32_e32 v100, v100, v101
	ds_bpermute_b32 v101, v204, v100
	s_waitcnt lgkmcnt(0)
	v_add_f32_e32 v100, v100, v101
	ds_bpermute_b32 v101, v205, v100
	s_waitcnt lgkmcnt(0)
	v_add_f32_e32 v100, v100, v101
	ds_bpermute_b32 v101, v206, v100
	s_waitcnt lgkmcnt(0)
	v_add_f32_e32 v100, v100, v101
	ds_bpermute_b32 v101, v207, v100
	s_waitcnt lgkmcnt(0)
	v_add_f32_e32 v106, v100, v101
	v_fmamk_f32 v153, v106, 0xb9800000, v153
	v_fmac_f32_e32 v152, 0xb9800000, v106
	v_fmamk_f32 v155, v106, 0xb9800000, v155
	v_fmac_f32_e32 v154, 0xb9800000, v106
	v_pk_mul_f32 v[98:99], v[154:155], v[154:155]
	v_pk_mul_f32 v[100:101], v[152:153], v[152:153]
	v_fmamk_f32 v149, v106, 0xb9800000, v149
	v_pk_mov_b32 v[102:103], v[100:101], v[98:99] op_sel:[1,0]
	v_mov_b32_e32 v101, v99
	v_pk_add_f32 v[98:99], v[102:103], v[100:101]
	v_fmac_f32_e32 v148, 0xb9800000, v106
	v_fmamk_f32 v151, v106, 0xb9800000, v151
	v_fmac_f32_e32 v150, 0xb9800000, v106
	v_pk_add_f32 v[98:99], v[98:99], v[98:99] op_sel_hi:[0,1]
	v_pk_mul_f32 v[100:101], v[150:151], v[150:151]
	v_pk_mul_f32 v[102:103], v[148:149], v[148:149]
	v_fmac_f32_e32 v144, 0xb9800000, v106
	v_pk_mov_b32 v[104:105], v[102:103], v[100:101] op_sel:[1,0]
	v_mov_b32_e32 v103, v101
	v_fmamk_f32 v145, v106, 0xb9800000, v145
	v_fmac_f32_e32 v146, 0xb9800000, v106
	v_mul_f32_e32 v98, v144, v144
	v_pk_add_f32 v[100:101], v[104:105], v[102:103]
	v_fmamk_f32 v147, v106, 0xb9800000, v147
	v_pk_fma_f32 v[102:103], v[144:145], v[144:145], v[98:99] op_sel_hi:[1,1,0]
	v_mul_f32_e32 v98, v146, v146
	v_pk_add_f32 v[100:101], v[100:101], v[100:101] op_sel_hi:[0,1]
	v_pk_fma_f32 v[104:105], v[146:147], v[146:147], v[98:99] op_sel_hi:[1,1,0]
	v_fmamk_f32 v143, v106, 0xb9800000, v143
	v_fmac_f32_e32 v142, 0xb9800000, v106
	v_fmamk_f32 v141, v106, 0xb9800000, v141
	v_fmac_f32_e32 v140, 0xb9800000, v106
	v_mul_f32_e32 v102, v140, v140
	v_mul_f32_e32 v104, v141, v141
	v_mul_f32_e32 v98, v142, v142
	v_mul_f32_e32 v100, v143, v143
	v_pk_add_f32 v[102:103], v[102:103], v[104:105]
	v_pk_add_f32 v[98:99], v[98:99], v[100:101]
	v_fmamk_f32 v137, v106, 0xb9800000, v137
	v_pk_add_f32 v[98:99], v[102:103], v[98:99]
	v_fmac_f32_e32 v136, 0xb9800000, v106
	v_fmamk_f32 v139, v106, 0xb9800000, v139
	v_fmac_f32_e32 v138, 0xb9800000, v106
	v_pk_add_f32 v[98:99], v[98:99], v[98:99] op_sel_hi:[0,1]
	v_pk_mul_f32 v[100:101], v[138:139], v[138:139]
	v_pk_mul_f32 v[102:103], v[136:137], v[136:137]
	v_fmac_f32_e32 v132, 0xb9800000, v106
	v_pk_mov_b32 v[104:105], v[102:103], v[100:101] op_sel:[1,0]
	v_mov_b32_e32 v103, v101
	v_fmamk_f32 v133, v106, 0xb9800000, v133
	v_fmac_f32_e32 v134, 0xb9800000, v106
	v_mul_f32_e32 v98, v132, v132
	v_pk_add_f32 v[100:101], v[104:105], v[102:103]
	v_fmamk_f32 v135, v106, 0xb9800000, v135
	v_pk_fma_f32 v[102:103], v[132:133], v[132:133], v[98:99] op_sel_hi:[1,1,0]
	v_mul_f32_e32 v98, v134, v134
	v_pk_add_f32 v[100:101], v[100:101], v[100:101] op_sel_hi:[0,1]
	v_pk_fma_f32 v[104:105], v[134:135], v[134:135], v[98:99] op_sel_hi:[1,1,0]
	v_fmamk_f32 v131, v106, 0xb9800000, v131
	v_fmac_f32_e32 v130, 0xb9800000, v106
	v_fmamk_f32 v129, v106, 0xb9800000, v129
	v_fmac_f32_e32 v128, 0xb9800000, v106
	v_mul_f32_e32 v102, v128, v128
	v_mul_f32_e32 v104, v129, v129
	v_mul_f32_e32 v100, v130, v130
	v_mul_f32_e32 v98, v131, v131
	v_pk_add_f32 v[102:103], v[102:103], v[104:105]
	v_pk_add_f32 v[98:99], v[100:101], v[98:99]
	v_fmamk_f32 v113, v106, 0xb9800000, v113
	v_pk_add_f32 v[98:99], v[102:103], v[98:99]
	v_fmac_f32_e32 v112, 0xb9800000, v106
	v_fmamk_f32 v115, v106, 0xb9800000, v115
	v_fmac_f32_e32 v114, 0xb9800000, v106
	v_pk_add_f32 v[98:99], v[98:99], v[98:99] op_sel_hi:[0,1]
	v_pk_mul_f32 v[100:101], v[114:115], v[114:115]
	v_pk_mul_f32 v[102:103], v[112:113], v[112:113]
	v_fmac_f32_e32 v94, 0xb9800000, v106
	v_pk_mov_b32 v[104:105], v[102:103], v[100:101] op_sel:[1,0]
	v_mov_b32_e32 v103, v101
	v_fmamk_f32 v95, v106, 0xb9800000, v95
	v_fmac_f32_e32 v96, 0xb9800000, v106
	v_mul_f32_e32 v98, v94, v94
	v_pk_add_f32 v[100:101], v[104:105], v[102:103]
	v_fmamk_f32 v97, v106, 0xb9800000, v97
	v_pk_fma_f32 v[102:103], v[94:95], v[94:95], v[98:99] op_sel_hi:[1,1,0]
	v_mul_f32_e32 v98, v96, v96
	v_pk_add_f32 v[100:101], v[100:101], v[100:101] op_sel_hi:[0,1]
	v_pk_fma_f32 v[104:105], v[96:97], v[96:97], v[98:99] op_sel_hi:[1,1,0]
	v_fmamk_f32 v93, v106, 0xb9800000, v93
	v_fmac_f32_e32 v92, 0xb9800000, v106
	v_fmamk_f32 v91, v106, 0xb9800000, v91
	v_fmac_f32_e32 v90, 0xb9800000, v106
	v_mul_f32_e32 v102, v90, v90
	v_mul_f32_e32 v104, v91, v91
	v_mul_f32_e32 v100, v92, v92
	v_mul_f32_e32 v98, v93, v93
	v_pk_add_f32 v[102:103], v[102:103], v[104:105]
	v_pk_add_f32 v[98:99], v[100:101], v[98:99]
	v_fmamk_f32 v87, v106, 0xb9800000, v87
	v_pk_add_f32 v[98:99], v[102:103], v[98:99]
	v_fmac_f32_e32 v86, 0xb9800000, v106
	v_fmamk_f32 v89, v106, 0xb9800000, v89
	v_fmac_f32_e32 v88, 0xb9800000, v106
	v_pk_add_f32 v[98:99], v[98:99], v[98:99] op_sel_hi:[0,1]
	v_pk_mul_f32 v[100:101], v[88:89], v[88:89]
	v_pk_mul_f32 v[102:103], v[86:87], v[86:87]
	v_fmac_f32_e32 v82, 0xb9800000, v106
	v_pk_mov_b32 v[104:105], v[102:103], v[100:101] op_sel:[1,0]
	v_mov_b32_e32 v103, v101
	v_fmamk_f32 v83, v106, 0xb9800000, v83
	v_fmac_f32_e32 v84, 0xb9800000, v106
	v_mul_f32_e32 v98, v82, v82
	v_pk_add_f32 v[100:101], v[104:105], v[102:103]
	v_fmamk_f32 v85, v106, 0xb9800000, v85
	v_pk_fma_f32 v[102:103], v[82:83], v[82:83], v[98:99] op_sel_hi:[1,1,0]
	v_mul_f32_e32 v98, v84, v84
	v_pk_add_f32 v[100:101], v[100:101], v[100:101] op_sel_hi:[0,1]
	v_pk_fma_f32 v[104:105], v[84:85], v[84:85], v[98:99] op_sel_hi:[1,1,0]
	v_fmamk_f32 v81, v106, 0xb9800000, v81
	v_fmac_f32_e32 v80, 0xb9800000, v106
	v_fmamk_f32 v79, v106, 0xb9800000, v79
	v_fmac_f32_e32 v78, 0xb9800000, v106
	v_mul_f32_e32 v102, v78, v78
	v_mul_f32_e32 v104, v79, v79
	v_mul_f32_e32 v100, v80, v80
	v_mul_f32_e32 v98, v81, v81
	v_pk_add_f32 v[102:103], v[102:103], v[104:105]
	v_pk_add_f32 v[98:99], v[100:101], v[98:99]
	v_fmamk_f32 v75, v106, 0xb9800000, v75
	v_pk_add_f32 v[98:99], v[102:103], v[98:99]
	v_fmac_f32_e32 v74, 0xb9800000, v106
	v_fmamk_f32 v77, v106, 0xb9800000, v77
	v_fmac_f32_e32 v76, 0xb9800000, v106
	v_pk_add_f32 v[98:99], v[98:99], v[98:99] op_sel_hi:[0,1]
	v_pk_mul_f32 v[100:101], v[76:77], v[76:77]
	v_pk_mul_f32 v[102:103], v[74:75], v[74:75]
	v_fmac_f32_e32 v70, 0xb9800000, v106
	v_pk_mov_b32 v[104:105], v[102:103], v[100:101] op_sel:[1,0]
	v_mov_b32_e32 v103, v101
	v_fmamk_f32 v71, v106, 0xb9800000, v71
	v_fmac_f32_e32 v72, 0xb9800000, v106
	v_mul_f32_e32 v98, v70, v70
	v_pk_add_f32 v[100:101], v[104:105], v[102:103]
	v_fmamk_f32 v73, v106, 0xb9800000, v73
	v_pk_fma_f32 v[102:103], v[70:71], v[70:71], v[98:99] op_sel_hi:[1,1,0]
	v_mul_f32_e32 v98, v72, v72
	v_pk_add_f32 v[100:101], v[100:101], v[100:101] op_sel_hi:[0,1]
	v_pk_fma_f32 v[104:105], v[72:73], v[72:73], v[98:99] op_sel_hi:[1,1,0]
	v_fmamk_f32 v69, v106, 0xb9800000, v69
	v_fmac_f32_e32 v68, 0xb9800000, v106
	v_fmamk_f32 v67, v106, 0xb9800000, v67
	v_fmac_f32_e32 v66, 0xb9800000, v106
	v_mul_f32_e32 v102, v66, v66
	v_mul_f32_e32 v104, v67, v67
	v_mul_f32_e32 v100, v68, v68
	v_mul_f32_e32 v98, v69, v69
	v_pk_add_f32 v[102:103], v[102:103], v[104:105]
	v_pk_add_f32 v[98:99], v[100:101], v[98:99]
	s_nop 0
	v_pk_add_f32 v[98:99], v[102:103], v[98:99]
	s_nop 0
	v_add_f32_e32 v98, v98, v99
	ds_bpermute_b32 v99, v202, v98
	s_waitcnt lgkmcnt(0)
	v_add_f32_e32 v98, v98, v99
	ds_bpermute_b32 v99, v203, v98
	s_waitcnt lgkmcnt(0)
	v_add_f32_e32 v98, v98, v99
	ds_bpermute_b32 v99, v204, v98
	s_waitcnt lgkmcnt(0)
	v_add_f32_e32 v98, v98, v99
	ds_bpermute_b32 v99, v205, v98
	s_waitcnt lgkmcnt(0)
	v_add_f32_e32 v98, v98, v99
	ds_bpermute_b32 v99, v206, v98
	s_waitcnt lgkmcnt(0)
	v_add_f32_e32 v98, v98, v99
	ds_bpermute_b32 v99, v207, v98
	s_waitcnt lgkmcnt(0)
	v_add_f32_e32 v98, v98, v99
	v_fmamk_f32 v98, v98, 0x39800000, v179
	v_mul_f32_e32 v99, 0x4f800000, v98
	v_cmp_gt_f32_e32 vcc, s79, v98
	s_nop 1
	v_cndmask_b32_e32 v98, v98, v99, vcc
	v_sqrt_f32_e32 v99, v98
	s_nop 0
	v_add_u32_e32 v100, -1, v99
	v_fma_f32 v101, -v100, v99, v98
	v_cmp_ge_f32_e64 s[0:1], 0, v101
	v_add_u32_e32 v101, 1, v99
	s_nop 0
	v_cndmask_b32_e64 v100, v99, v100, s[0:1]
	v_fma_f32 v99, -v101, v99, v98
	v_cmp_lt_f32_e64 s[0:1], 0, v99
	s_nop 1
	v_cndmask_b32_e64 v99, v100, v101, s[0:1]
	v_mul_f32_e32 v100, 0x37800000, v99
	v_cndmask_b32_e32 v99, v99, v100, vcc
	v_cmp_class_f32_e32 vcc, v98, v242
	s_nop 1
	v_cndmask_b32_e32 v98, v99, v98, vcc
	v_div_scale_f32 v99, s[0:1], v98, v98, 1.0
	v_rcp_f32_e32 v100, v99
	s_lshl_b64 s[0:1], s[46:47], 12
	s_and_b64 s[8:9], s[48:49], exec
	s_cselect_b32 s2, 0, s2
	v_fma_f32 v101, -v99, v100, 1.0
	v_fmac_f32_e32 v100, v101, v100
	v_div_scale_f32 v101, vcc, 1.0, v98, 1.0
	v_mul_f32_e32 v102, v101, v100
	v_fma_f32 v103, -v99, v102, v101
	v_fmac_f32_e32 v102, v103, v100
	v_fma_f32 v99, -v99, v102, v101
	v_div_fmas_f32 v104, v99, v100, v102
	v_add_u32_e32 v99, s2, v241
	ds_read_b128 v[100:103], v99 offset:49152
	ds_read_b128 v[108:111], v99 offset:50176
	v_div_fixup_f32 v98, v104, v98, 1.0
	ds_read_b128 v[104:107], v99 offset:32768
	ds_read_b128 v[116:119], v99 offset:33792
	v_pk_mul_f32 v[120:121], v[152:153], v[98:99] op_sel_hi:[1,0]
	s_waitcnt lgkmcnt(3)
	v_pk_add_f32 v[100:101], v[100:101], 1.0 op_sel_hi:[1,0]
	v_pk_add_f32 v[102:103], v[102:103], 1.0 op_sel_hi:[1,0]
	s_waitcnt lgkmcnt(1)
	v_pk_fma_f32 v[104:105], v[100:101], v[120:121], v[104:105]
	v_mov_b32_e32 v120, v193
	v_cvt_pk_fp8_f32 v120, v104, v105
	v_pk_mul_f32 v[100:101], v[154:155], v[98:99] op_sel_hi:[1,0]
	v_pk_add_f32 v[108:109], v[108:109], 1.0 op_sel_hi:[1,0]
	v_pk_fma_f32 v[106:107], v[102:103], v[100:101], v[106:107]
	v_lshl_add_u64 v[100:101], v[198:199], 0, s[0:1]
	v_cvt_pk_fp8_f32 v120, v106, v107 op_sel:[0,0,1]
	v_pk_add_f32 v[110:111], v[110:111], 1.0 op_sel_hi:[1,0]
	s_lshl_b64 s[0:1], s[46:47], 13
	v_lshl_add_u64 v[102:103], v[194:195], 0, s[0:1]
	global_store_dword v[100:101], v120, off
	v_bfe_u32 v120, v104, 16, 1
	v_add3_u32 v104, v104, v120, s80
	v_bfe_u32 v120, v105, 16, 1
	v_add3_u32 v105, v105, v120, s80
	v_pk_mul_f32 v[120:121], v[148:149], v[98:99] op_sel_hi:[1,0]
	v_lshrrev_b32_e32 v104, 16, v104
	s_waitcnt lgkmcnt(0)
	v_pk_fma_f32 v[108:109], v[108:109], v[120:121], v[116:117]
	v_mov_b32_e32 v120, v193
	v_cvt_pk_fp8_f32 v120, v108, v109
	v_pk_mul_f32 v[116:117], v[150:151], v[98:99] op_sel_hi:[1,0]
	v_and_or_b32 v104, v105, s76, v104
	v_bfe_u32 v105, v106, 16, 1
	v_pk_fma_f32 v[124:125], v[110:111], v[116:117], v[118:119]
	v_add3_u32 v105, v106, v105, s80
	v_bfe_u32 v106, v107, 16, 1
	v_cvt_pk_fp8_f32 v120, v124, v125 op_sel:[0,0,1]
	v_lshrrev_b32_e32 v105, 16, v105
	v_add3_u32 v106, v107, v106, s80
	v_and_or_b32 v105, v106, s76, v105
	global_store_dwordx2 v[102:103], v[104:105], off
	global_store_dword v[100:101], v120, off offset:256
	v_bfe_u32 v104, v108, 16, 1
	v_add3_u32 v104, v108, v104, s80
	v_bfe_u32 v105, v109, 16, 1
	v_lshrrev_b32_e32 v104, 16, v104
	v_add3_u32 v105, v109, v105, s80
	v_and_or_b32 v126, v105, s76, v104
	v_bfe_u32 v104, v124, 16, 1
	v_add3_u32 v104, v124, v104, s80
	v_lshrrev_b32_e32 v124, 16, v104
	ds_read_b128 v[104:107], v99 offset:51200
	ds_read_b128 v[116:119], v99 offset:52224
	ds_read_b128 v[108:111], v99 offset:34816
	ds_read_b128 v[120:123], v99 offset:35840
	v_pk_mul_f32 v[144:145], v[144:145], v[98:99] op_sel_hi:[1,0]
	s_waitcnt lgkmcnt(3)
	v_pk_add_f32 v[104:105], v[104:105], 1.0 op_sel_hi:[1,0]
	v_bfe_u32 v127, v125, 16, 1
	s_waitcnt lgkmcnt(1)
	v_pk_fma_f32 v[104:105], v[104:105], v[144:145], v[108:109]
	v_pk_mul_f32 v[108:109], v[146:147], v[98:99] op_sel_hi:[1,0]
	v_pk_add_f32 v[106:107], v[106:107], 1.0 op_sel_hi:[1,0]
	v_mov_b32_e32 v144, v193
	v_pk_fma_f32 v[106:107], v[106:107], v[108:109], v[110:111]
	v_add3_u32 v108, v125, v127, s80
	v_and_or_b32 v127, v108, s76, v124
	v_bfe_u32 v108, v104, 16, 1
	v_cvt_pk_fp8_f32 v144, v104, v105
	v_add3_u32 v104, v104, v108, s80
	v_bfe_u32 v108, v105, 16, 1
	v_add3_u32 v105, v105, v108, s80
	v_pk_mul_f32 v[108:109], v[140:141], v[98:99] op_sel_hi:[1,0]
	v_pk_add_f32 v[110:111], v[116:117], 1.0 op_sel_hi:[1,0]
	v_lshrrev_b32_e32 v104, 16, v104
	s_waitcnt lgkmcnt(0)
	v_pk_fma_f32 v[108:109], v[110:111], v[108:109], v[120:121]
	v_mov_b32_e32 v120, v193
	v_cvt_pk_fp8_f32 v120, v108, v109
	v_pk_mul_f32 v[110:111], v[142:143], v[98:99] op_sel_hi:[1,0]
	v_pk_add_f32 v[116:117], v[118:119], 1.0 op_sel_hi:[1,0]
	v_and_or_b32 v104, v105, s76, v104
	v_bfe_u32 v105, v106, 16, 1
	v_pk_fma_f32 v[110:111], v[116:117], v[110:111], v[122:123]
	v_cvt_pk_fp8_f32 v144, v106, v107 op_sel:[0,0,1]
	v_add3_u32 v105, v106, v105, s80
	v_bfe_u32 v106, v107, 16, 1
	v_cvt_pk_fp8_f32 v120, v110, v111 op_sel:[0,0,1]
	v_lshrrev_b32_e32 v105, 16, v105
	v_add3_u32 v106, v107, v106, s80
	v_and_or_b32 v105, v106, s76, v105
	global_store_dwordx2 v[102:103], v[126:127], off offset:512
	global_store_dword v[100:101], v144, off offset:512
	global_store_dwordx2 v[102:103], v[104:105], off offset:1024
	global_store_dword v[100:101], v120, off offset:768
	v_bfe_u32 v104, v108, 16, 1
	v_add3_u32 v104, v108, v104, s80
	v_bfe_u32 v105, v109, 16, 1
	v_lshrrev_b32_e32 v104, 16, v104
	v_add3_u32 v105, v109, v105, s80
	v_and_or_b32 v104, v105, s76, v104
	v_bfe_u32 v105, v110, 16, 1
	v_add3_u32 v105, v110, v105, s80
	v_bfe_u32 v106, v111, 16, 1
	v_lshrrev_b32_e32 v105, 16, v105
	v_add3_u32 v106, v111, v106, s80
	v_and_or_b32 v105, v106, s76, v105
	global_store_dwordx2 v[102:103], v[104:105], off offset:1536
	ds_read_b128 v[104:107], v99 offset:53248
	ds_read_b128 v[108:111], v99 offset:36864
	v_pk_mul_f32 v[124:125], v[136:137], v[98:99] op_sel_hi:[1,0]
	ds_read_b128 v[116:119], v99 offset:54272
	ds_read_b128 v[120:123], v99 offset:37888
	s_waitcnt lgkmcnt(3)
	v_pk_add_f32 v[104:105], v[104:105], 1.0 op_sel_hi:[1,0]
	v_pk_add_f32 v[106:107], v[106:107], 1.0 op_sel_hi:[1,0]
	s_waitcnt lgkmcnt(2)
	v_pk_fma_f32 v[104:105], v[104:105], v[124:125], v[108:109]
	v_mov_b32_e32 v124, v193
	v_cvt_pk_fp8_f32 v124, v104, v105
	v_pk_mul_f32 v[108:109], v[138:139], v[98:99] op_sel_hi:[1,0]
	v_pk_mul_f32 v[128:129], v[128:129], v[98:99] op_sel_hi:[1,0]
	v_pk_fma_f32 v[106:107], v[106:107], v[108:109], v[110:111]
	v_bfe_u32 v108, v104, 16, 1
	v_add3_u32 v104, v104, v108, s80
	v_bfe_u32 v108, v105, 16, 1
	v_add3_u32 v105, v105, v108, s80
	v_pk_mul_f32 v[108:109], v[132:133], v[98:99] op_sel_hi:[1,0]
	s_waitcnt lgkmcnt(1)
	v_pk_add_f32 v[110:111], v[116:117], 1.0 op_sel_hi:[1,0]
	v_cvt_pk_fp8_f32 v124, v106, v107 op_sel:[0,0,1]
	s_waitcnt lgkmcnt(0)
	v_pk_fma_f32 v[108:109], v[108:109], v[110:111], v[120:121]
	v_mov_b32_e32 v120, v193
	v_cvt_pk_fp8_f32 v120, v108, v109
	v_lshrrev_b32_e32 v104, 16, v104
	v_pk_mul_f32 v[110:111], v[134:135], v[98:99] op_sel_hi:[1,0]
	v_pk_add_f32 v[116:117], v[118:119], 1.0 op_sel_hi:[1,0]
	global_store_dword v[100:101], v124, off offset:1024
	v_and_or_b32 v104, v105, s76, v104
	v_bfe_u32 v105, v106, 16, 1
	v_pk_fma_f32 v[124:125], v[110:111], v[116:117], v[122:123]
	v_add3_u32 v105, v106, v105, s80
	v_bfe_u32 v106, v107, 16, 1
	v_cvt_pk_fp8_f32 v120, v124, v125 op_sel:[0,0,1]
	v_lshrrev_b32_e32 v105, 16, v105
	v_add3_u32 v106, v107, v106, s80
	v_and_or_b32 v105, v106, s76, v105
	global_store_dwordx2 v[102:103], v[104:105], off offset:2048
	global_store_dword v[100:101], v120, off offset:1280
	v_bfe_u32 v104, v108, 16, 1
	v_add3_u32 v104, v108, v104, s80
	v_bfe_u32 v105, v109, 16, 1
	v_lshrrev_b32_e32 v104, 16, v104
	v_add3_u32 v105, v109, v105, s80
	v_and_or_b32 v126, v105, s76, v104
	v_bfe_u32 v104, v124, 16, 1
	v_add3_u32 v104, v124, v104, s80
	v_lshrrev_b32_e32 v124, 16, v104
	ds_read_b128 v[104:107], v99 offset:55296
	ds_read_b128 v[116:119], v99 offset:56320
	ds_read_b128 v[108:111], v99 offset:38912
	ds_read_b128 v[120:123], v99 offset:39936
	v_bfe_u32 v127, v125, 16, 1
	s_waitcnt lgkmcnt(3)
	v_pk_add_f32 v[104:105], v[104:105], 1.0 op_sel_hi:[1,0]
	v_pk_add_f32 v[106:107], v[106:107], 1.0 op_sel_hi:[1,0]
	s_waitcnt lgkmcnt(1)
	v_pk_fma_f32 v[104:105], v[128:129], v[104:105], v[108:109]
	v_pk_mul_f32 v[108:109], v[130:131], v[98:99] op_sel_hi:[1,0]
	v_mov_b32_e32 v128, v193
	v_pk_fma_f32 v[106:107], v[108:109], v[106:107], v[110:111]
	v_add3_u32 v108, v125, v127, s80
	v_and_or_b32 v127, v108, s76, v124
	v_bfe_u32 v108, v104, 16, 1
	v_cvt_pk_fp8_f32 v128, v104, v105
	v_add3_u32 v104, v104, v108, s80
	v_bfe_u32 v108, v105, 16, 1
	v_add3_u32 v105, v105, v108, s80
	v_pk_mul_f32 v[108:109], v[112:113], v[98:99] op_sel_hi:[1,0]
	v_pk_add_f32 v[110:111], v[116:117], 1.0 op_sel_hi:[1,0]
	v_mov_b32_e32 v116, v193
	s_waitcnt lgkmcnt(0)
	v_pk_fma_f32 v[108:109], v[108:109], v[110:111], v[120:121]
	v_lshrrev_b32_e32 v104, 16, v104
	v_cvt_pk_fp8_f32 v116, v108, v109
	v_pk_mul_f32 v[110:111], v[114:115], v[98:99] op_sel_hi:[1,0]
	v_pk_add_f32 v[112:113], v[118:119], 1.0 op_sel_hi:[1,0]
	v_and_or_b32 v104, v105, s76, v104
	v_bfe_u32 v105, v106, 16, 1
	v_pk_fma_f32 v[110:111], v[110:111], v[112:113], v[122:123]
	v_cvt_pk_fp8_f32 v128, v106, v107 op_sel:[0,0,1]
	v_add3_u32 v105, v106, v105, s80
	v_bfe_u32 v106, v107, 16, 1
	v_cvt_pk_fp8_f32 v116, v110, v111 op_sel:[0,0,1]
	v_lshrrev_b32_e32 v105, 16, v105
	v_add3_u32 v106, v107, v106, s80
	v_and_or_b32 v105, v106, s76, v105
	global_store_dwordx2 v[102:103], v[126:127], off offset:2560
	global_store_dword v[100:101], v128, off offset:1536
	global_store_dwordx2 v[102:103], v[104:105], off offset:3072
	global_store_dword v[100:101], v116, off offset:1792
	v_bfe_u32 v104, v108, 16, 1
	v_add3_u32 v104, v108, v104, s80
	v_bfe_u32 v105, v109, 16, 1
	v_lshrrev_b32_e32 v104, 16, v104
	v_add3_u32 v105, v109, v105, s80
	v_and_or_b32 v104, v105, s76, v104
	v_bfe_u32 v105, v110, 16, 1
	v_add3_u32 v105, v110, v105, s80
	v_bfe_u32 v106, v111, 16, 1
	v_lshrrev_b32_e32 v105, 16, v105
	v_add3_u32 v106, v111, v106, s80
	v_and_or_b32 v105, v106, s76, v105
	global_store_dwordx2 v[102:103], v[104:105], off offset:3584
	ds_read_b128 v[104:107], v99 offset:57344
	ds_read_b128 v[108:111], v99 offset:40960
	v_pk_mul_f32 v[94:95], v[94:95], v[98:99] op_sel_hi:[1,0]
	v_pk_mul_f32 v[96:97], v[96:97], v[98:99] op_sel_hi:[1,0]
	ds_read_b128 v[112:115], v99 offset:58368
	ds_read_b128 v[116:119], v99 offset:41984
	s_waitcnt lgkmcnt(3)
	v_pk_add_f32 v[104:105], v[104:105], 1.0 op_sel_hi:[1,0]
	v_pk_mul_f32 v[90:91], v[90:91], v[98:99] op_sel_hi:[1,0]
	s_waitcnt lgkmcnt(2)
	v_pk_fma_f32 v[94:95], v[94:95], v[104:105], v[108:109]
	v_mov_b32_e32 v108, v193
	v_pk_add_f32 v[104:105], v[106:107], 1.0 op_sel_hi:[1,0]
	v_cvt_pk_fp8_f32 v108, v94, v95
	v_pk_fma_f32 v[96:97], v[96:97], v[104:105], v[110:111]
	v_bfe_u32 v104, v94, 16, 1
	v_add3_u32 v94, v94, v104, s80
	v_bfe_u32 v104, v95, 16, 1
	v_lshrrev_b32_e32 v94, 16, v94
	v_add3_u32 v95, v95, v104, s80
	v_and_or_b32 v94, v95, s76, v94
	v_bfe_u32 v95, v96, 16, 1
	v_cvt_pk_fp8_f32 v108, v96, v97 op_sel:[0,0,1]
	v_add3_u32 v95, v96, v95, s80
	v_bfe_u32 v96, v97, 16, 1
	v_lshrrev_b32_e32 v95, 16, v95
	v_add3_u32 v96, v97, v96, s80
	v_and_or_b32 v95, v96, s76, v95
	s_waitcnt lgkmcnt(1)
	v_pk_add_f32 v[96:97], v[112:113], 1.0 op_sel_hi:[1,0]
	v_mov_b32_e32 v104, v193
	s_waitcnt lgkmcnt(0)
	v_pk_fma_f32 v[96:97], v[90:91], v[96:97], v[116:117]
	v_pk_mul_f32 v[90:91], v[92:93], v[98:99] op_sel_hi:[1,0]
	v_cvt_pk_fp8_f32 v104, v96, v97
	v_pk_add_f32 v[92:93], v[114:115], 1.0 op_sel_hi:[1,0]
	global_store_dword v[100:101], v108, off offset:2048
	v_pk_fma_f32 v[114:115], v[90:91], v[92:93], v[118:119]
	v_bfe_u32 v92, v96, 16, 1
	v_cvt_pk_fp8_f32 v104, v114, v115 op_sel:[0,0,1]
	v_add3_u32 v92, v96, v92, s80
	v_bfe_u32 v93, v97, 16, 1
	v_add_co_u32_e32 v90, vcc, s77, v102
	v_lshrrev_b32_e32 v92, 16, v92
	v_add3_u32 v93, v97, v93, s80
	v_addc_co_u32_e32 v91, vcc, 0, v103, vcc
	v_and_or_b32 v96, v93, s76, v92
	v_bfe_u32 v92, v114, 16, 1
	global_store_dwordx2 v[90:91], v[94:95], off
	global_store_dword v[100:101], v104, off offset:2304
	v_add3_u32 v92, v114, v92, s80
	v_lshrrev_b32_e32 v97, 16, v92
	ds_read_b128 v[92:95], v99 offset:59392
	ds_read_b128 v[106:109], v99 offset:60416
	ds_read_b128 v[102:105], v99 offset:43008
	ds_read_b128 v[110:113], v99 offset:44032
	v_pk_mul_f32 v[86:87], v[86:87], v[98:99] op_sel_hi:[1,0]
	s_waitcnt lgkmcnt(3)
	v_pk_add_f32 v[92:93], v[92:93], 1.0 op_sel_hi:[1,0]
	v_bfe_u32 v114, v115, 16, 1
	s_waitcnt lgkmcnt(1)
	v_pk_fma_f32 v[86:87], v[86:87], v[92:93], v[102:103]
	v_pk_mul_f32 v[88:89], v[88:89], v[98:99] op_sel_hi:[1,0]
	v_pk_add_f32 v[92:93], v[94:95], 1.0 op_sel_hi:[1,0]
	v_mov_b32_e32 v102, v193
	v_pk_fma_f32 v[88:89], v[88:89], v[92:93], v[104:105]
	v_add3_u32 v92, v115, v114, s80
	v_and_or_b32 v97, v92, s76, v97
	v_bfe_u32 v92, v86, 16, 1
	v_cvt_pk_fp8_f32 v102, v86, v87
	v_add3_u32 v86, v86, v92, s80
	v_bfe_u32 v92, v87, 16, 1
	v_add3_u32 v87, v87, v92, s80
	v_pk_mul_f32 v[82:83], v[82:83], v[98:99] op_sel_hi:[1,0]
	v_pk_add_f32 v[92:93], v[106:107], 1.0 op_sel_hi:[1,0]
	v_mov_b32_e32 v94, v193
	s_waitcnt lgkmcnt(0)
	v_pk_fma_f32 v[82:83], v[82:83], v[92:93], v[110:111]
	v_lshrrev_b32_e32 v86, 16, v86
	v_cvt_pk_fp8_f32 v94, v82, v83
	v_pk_mul_f32 v[84:85], v[84:85], v[98:99] op_sel_hi:[1,0]
	v_pk_add_f32 v[92:93], v[108:109], 1.0 op_sel_hi:[1,0]
	v_and_or_b32 v86, v87, s76, v86
	v_bfe_u32 v87, v88, 16, 1
	v_pk_fma_f32 v[84:85], v[84:85], v[92:93], v[112:113]
	v_cvt_pk_fp8_f32 v102, v88, v89 op_sel:[0,0,1]
	v_add3_u32 v87, v88, v87, s80
	v_bfe_u32 v88, v89, 16, 1
	v_cvt_pk_fp8_f32 v94, v84, v85 op_sel:[0,0,1]
	v_lshrrev_b32_e32 v87, 16, v87
	v_add3_u32 v88, v89, v88, s80
	v_and_or_b32 v87, v88, s76, v87
	global_store_dwordx2 v[90:91], v[96:97], off offset:512
	global_store_dword v[100:101], v102, off offset:2560
	global_store_dwordx2 v[90:91], v[86:87], off offset:1024
	global_store_dword v[100:101], v94, off offset:2816
	v_bfe_u32 v86, v82, 16, 1
	v_add3_u32 v82, v82, v86, s80
	v_bfe_u32 v86, v83, 16, 1
	v_lshrrev_b32_e32 v82, 16, v82
	v_add3_u32 v83, v83, v86, s80
	v_and_or_b32 v82, v83, s76, v82
	v_bfe_u32 v83, v84, 16, 1
	v_add3_u32 v83, v84, v83, s80
	v_bfe_u32 v84, v85, 16, 1
	v_lshrrev_b32_e32 v83, 16, v83
	v_add3_u32 v84, v85, v84, s80
	v_and_or_b32 v83, v84, s76, v83
	global_store_dwordx2 v[90:91], v[82:83], off offset:1536
	ds_read_b128 v[82:85], v99 offset:61440
	ds_read_b128 v[86:89], v99 offset:45056
	ds_read_b128 v[92:95], v99 offset:62464
	ds_read_b128 v[102:105], v99 offset:46080
	v_pk_mul_f32 v[78:79], v[78:79], v[98:99] op_sel_hi:[1,0]
	s_waitcnt lgkmcnt(3)
	v_pk_add_f32 v[82:83], v[82:83], 1.0 op_sel_hi:[1,0]
	v_pk_mul_f32 v[80:81], v[80:81], v[98:99] op_sel_hi:[1,0]
	s_waitcnt lgkmcnt(2)
	v_pk_fma_f32 v[78:79], v[78:79], v[82:83], v[86:87]
	v_pk_add_f32 v[82:83], v[84:85], 1.0 op_sel_hi:[1,0]
	v_mov_b32_e32 v86, v193
	v_pk_fma_f32 v[80:81], v[80:81], v[82:83], v[88:89]
	v_bfe_u32 v82, v78, 16, 1
	v_cvt_pk_fp8_f32 v86, v78, v79
	v_add3_u32 v78, v78, v82, s80
	v_bfe_u32 v82, v79, 16, 1
	v_add3_u32 v79, v79, v82, s80
	v_pk_mul_f32 v[74:75], v[74:75], v[98:99] op_sel_hi:[1,0]
	s_waitcnt lgkmcnt(1)
	v_pk_add_f32 v[82:83], v[92:93], 1.0 op_sel_hi:[1,0]
	v_lshrrev_b32_e32 v78, 16, v78
	s_waitcnt lgkmcnt(0)
	v_pk_fma_f32 v[74:75], v[74:75], v[82:83], v[102:103]
	v_mov_b32_e32 v84, v193
	v_and_or_b32 v78, v79, s76, v78
	v_bfe_u32 v79, v80, 16, 1
	v_cvt_pk_fp8_f32 v84, v74, v75
	v_cvt_pk_fp8_f32 v86, v80, v81 op_sel:[0,0,1]
	v_add3_u32 v79, v80, v79, s80
	v_bfe_u32 v80, v81, 16, 1
	v_pk_mul_f32 v[76:77], v[76:77], v[98:99] op_sel_hi:[1,0]
	v_pk_add_f32 v[82:83], v[94:95], 1.0 op_sel_hi:[1,0]
	v_lshrrev_b32_e32 v79, 16, v79
	v_pk_fma_f32 v[92:93], v[76:77], v[82:83], v[104:105]
	v_add3_u32 v76, v81, v80, s80
	v_and_or_b32 v79, v76, s76, v79
	v_bfe_u32 v76, v74, 16, 1
	v_cvt_pk_fp8_f32 v84, v92, v93 op_sel:[0,0,1]
	v_add3_u32 v74, v74, v76, s80
	v_bfe_u32 v76, v75, 16, 1
	v_lshrrev_b32_e32 v74, 16, v74
	v_add3_u32 v75, v75, v76, s80
	v_and_or_b32 v94, v75, s76, v74
	v_bfe_u32 v74, v92, 16, 1
	global_store_dword v[100:101], v86, off offset:3072
	global_store_dwordx2 v[90:91], v[78:79], off offset:2048
	global_store_dword v[100:101], v84, off offset:3328
	v_add3_u32 v74, v92, v74, s80
	v_lshrrev_b32_e32 v92, 16, v74
	ds_read_b128 v[74:77], v99 offset:63488
	ds_read_b128 v[82:85], v99 offset:64512
	ds_read_b128 v[78:81], v99 offset:47104
	ds_read_b128 v[86:89], v99 offset:48128
	v_pk_mul_f32 v[70:71], v[70:71], v[98:99] op_sel_hi:[1,0]
	s_waitcnt lgkmcnt(3)
	v_pk_add_f32 v[74:75], v[74:75], 1.0 op_sel_hi:[1,0]
	v_bfe_u32 v95, v93, 16, 1
	s_waitcnt lgkmcnt(1)
	v_pk_fma_f32 v[70:71], v[70:71], v[74:75], v[78:79]
	v_pk_mul_f32 v[72:73], v[72:73], v[98:99] op_sel_hi:[1,0]
	v_pk_add_f32 v[74:75], v[76:77], 1.0 op_sel_hi:[1,0]
	v_mov_b32_e32 v78, v193
	v_pk_fma_f32 v[72:73], v[72:73], v[74:75], v[80:81]
	v_add3_u32 v74, v93, v95, s80
	v_and_or_b32 v95, v74, s76, v92
	v_bfe_u32 v74, v70, 16, 1
	v_cvt_pk_fp8_f32 v78, v70, v71
	v_add3_u32 v70, v70, v74, s80
	v_bfe_u32 v74, v71, 16, 1
	v_add3_u32 v71, v71, v74, s80
	v_pk_mul_f32 v[66:67], v[66:67], v[98:99] op_sel_hi:[1,0]
	v_pk_add_f32 v[74:75], v[82:83], 1.0 op_sel_hi:[1,0]
	v_mov_b32_e32 v76, v193
	s_waitcnt lgkmcnt(0)
	v_pk_fma_f32 v[66:67], v[66:67], v[74:75], v[86:87]
	v_lshrrev_b32_e32 v70, 16, v70
	v_cvt_pk_fp8_f32 v76, v66, v67
	v_pk_mul_f32 v[68:69], v[68:69], v[98:99] op_sel_hi:[1,0]
	v_pk_add_f32 v[74:75], v[84:85], 1.0 op_sel_hi:[1,0]
	v_and_or_b32 v70, v71, s76, v70
	v_bfe_u32 v71, v72, 16, 1
	v_pk_fma_f32 v[68:69], v[68:69], v[74:75], v[88:89]
	v_cvt_pk_fp8_f32 v78, v72, v73 op_sel:[0,0,1]
	v_add3_u32 v71, v72, v71, s80
	v_bfe_u32 v72, v73, 16, 1
	v_cvt_pk_fp8_f32 v76, v68, v69 op_sel:[0,0,1]
	v_lshrrev_b32_e32 v71, 16, v71
	v_add3_u32 v72, v73, v72, s80
	v_and_or_b32 v71, v72, s76, v71
	global_store_dwordx2 v[90:91], v[94:95], off offset:2560
	global_store_dword v[100:101], v78, off offset:3584
	global_store_dwordx2 v[90:91], v[70:71], off offset:3072
	global_store_dword v[100:101], v76, off offset:3840
	v_bfe_u32 v70, v66, 16, 1
	v_add3_u32 v66, v66, v70, s80
	v_bfe_u32 v70, v67, 16, 1
	v_lshrrev_b32_e32 v66, 16, v66
	v_add3_u32 v67, v67, v70, s80
	v_and_or_b32 v66, v67, s76, v66
	v_bfe_u32 v67, v68, 16, 1
	v_add3_u32 v67, v68, v67, s80
	v_bfe_u32 v68, v69, 16, 1
	v_lshrrev_b32_e32 v67, 16, v67
	v_add3_u32 v68, v69, v68, s80
	v_and_or_b32 v67, v68, s76, v67
	global_store_dwordx2 v[90:91], v[66:67], off offset:3584
	s_add_u32 s26, s26, s34
	s_addc_u32 s27, s27, s35
	s_add_u32 s4, s4, s6
	s_addc_u32 s5, s5, s7
	s_add_i32 s69, s69, s74
	s_andn2_b64 vcc, exec, s[52:53]
	s_mov_b32 s46, s50
	s_cbranch_vccz .LBB0_374

.LBB0_868:
	v_add_f32_e32 v130, v126, v127
	v_add_f32_e32 v131, v128, v129
	v_add_f32_e32 v130, v130, v131
	v_and_b32_e32 v131, 64, v241
	v_add_u32_e32 v131, 64, v131
	v_xor_b32_e32 v132, 1, v241
	v_cmp_lt_i32_e32 vcc, v132, v131
	v_add_f32_e32 v130, v242, v130
	s_and_b32 s2, s19, 0xffff8000
	v_cndmask_b32_e32 v132, v241, v132, vcc
	v_lshlrev_b32_e32 v185, 2, v132
	ds_bpermute_b32 v132, v185, v130
	s_add_i32 s2, s2, 0x8000
	s_waitcnt lgkmcnt(0)
	v_add_f32_e32 v130, v130, v132
	v_xor_b32_e32 v132, 2, v241
	v_cmp_lt_i32_e32 vcc, v132, v131
	s_nop 1
	v_cndmask_b32_e32 v132, v241, v132, vcc
	v_lshlrev_b32_e32 v190, 2, v132
	ds_bpermute_b32 v132, v190, v130
	s_waitcnt lgkmcnt(0)
	v_add_f32_e32 v130, v130, v132
	v_xor_b32_e32 v132, 4, v241
	v_cmp_lt_i32_e32 vcc, v132, v131
	s_nop 1
	v_cndmask_b32_e32 v132, v241, v132, vcc
	v_lshlrev_b32_e32 v191, 2, v132
	ds_bpermute_b32 v132, v191, v130
	s_waitcnt lgkmcnt(0)
	v_add_f32_e32 v130, v130, v132
	v_xor_b32_e32 v132, 8, v241
	v_cmp_lt_i32_e32 vcc, v132, v131
	s_nop 1
	v_cndmask_b32_e32 v132, v241, v132, vcc
	v_lshlrev_b32_e32 v192, 2, v132
	ds_bpermute_b32 v132, v192, v130
	s_waitcnt lgkmcnt(0)
	v_add_f32_e32 v130, v130, v132
	v_xor_b32_e32 v132, 16, v241
	v_cmp_lt_i32_e32 vcc, v132, v131
	s_nop 1
	v_cndmask_b32_e32 v132, v241, v132, vcc
	v_lshlrev_b32_e32 v193, 2, v132
	ds_bpermute_b32 v132, v193, v130
	s_waitcnt lgkmcnt(0)
	v_add_f32_e32 v130, v130, v132
	v_xor_b32_e32 v132, 32, v241
	v_cmp_lt_i32_e32 vcc, v132, v131
	s_nop 1
	v_cndmask_b32_e32 v131, v241, v132, vcc
	v_lshlrev_b32_e32 v194, 2, v131
	ds_bpermute_b32 v131, v194, v130
	s_waitcnt lgkmcnt(0)
	v_add_f32_e32 v182, v130, v131
	v_fmamk_f32 v87, v182, 0xb9800000, v87
	v_fmamk_f32 v86, v182, 0xb9800000, v86
	v_fmamk_f32 v89, v182, 0xb9800000, v89
	v_fmac_f32_e32 v88, 0xb9800000, v182
	v_pk_mul_f32 v[130:131], v[88:89], v[88:89]
	v_pk_mul_f32 v[132:133], v[86:87], v[86:87]
	v_fmamk_f32 v189, v182, 0xb9800000, v79
	v_pk_mov_b32 v[134:135], v[132:133], v[130:131] op_sel:[1,0]
	v_mov_b32_e32 v133, v131
	v_fmamk_f32 v188, v182, 0xb9800000, v78
	v_fmamk_f32 v81, v182, 0xb9800000, v81
	v_fmac_f32_e32 v80, 0xb9800000, v182
	v_pk_add_f32 v[130:131], v[134:135], v[132:133]
	v_pk_mul_f32 v[78:79], v[80:81], v[80:81]
	v_pk_mul_f32 v[132:133], v[188:189], v[188:189]
	v_fmac_f32_e32 v76, 0xb9800000, v182
	v_pk_mov_b32 v[134:135], v[132:133], v[78:79] op_sel:[1,0]
	v_mov_b32_e32 v133, v79
	v_pk_add_f32 v[78:79], v[134:135], v[132:133]
	v_fmamk_f32 v77, v182, 0xb9800000, v77
	v_pk_add_f32 v[132:133], v[78:79], v[78:79] op_sel_hi:[0,1]
	v_fmamk_f32 v78, v182, 0xb9800000, v74
	v_fmamk_f32 v79, v182, 0xb9800000, v75
	v_mul_f32_e32 v74, v78, v78
	v_pk_fma_f32 v[134:135], v[78:79], v[78:79], v[74:75] op_sel_hi:[1,1,0]
	v_mul_f32_e32 v74, v76, v76
	v_pk_add_f32 v[130:131], v[130:131], v[130:131] op_sel_hi:[0,1]
	v_pk_fma_f32 v[136:137], v[76:77], v[76:77], v[74:75] op_sel_hi:[1,1,0]
	v_fmamk_f32 v75, v182, 0xb9800000, v85
	v_fmamk_f32 v74, v182, 0xb9800000, v84
	v_fmamk_f32 v83, v182, 0xb9800000, v83
	v_fmac_f32_e32 v82, 0xb9800000, v182
	v_mul_f32_e32 v134, v82, v82
	v_mul_f32_e32 v136, v83, v83
	v_mul_f32_e32 v130, v74, v74
	v_mul_f32_e32 v132, v75, v75
	v_pk_add_f32 v[84:85], v[134:135], v[136:137]
	v_pk_add_f32 v[130:131], v[130:131], v[132:133]
	v_fmamk_f32 v71, v182, 0xb9800000, v71
	v_fmamk_f32 v70, v182, 0xb9800000, v70
	v_fmamk_f32 v73, v182, 0xb9800000, v73
	v_fmac_f32_e32 v72, 0xb9800000, v182
	v_fmamk_f32 v186, v182, 0xb9800000, v66
	v_pk_add_f32 v[84:85], v[84:85], v[130:131]
	v_pk_mul_f32 v[130:131], v[72:73], v[72:73]
	v_pk_mul_f32 v[132:133], v[70:71], v[70:71]
	v_fmamk_f32 v187, v182, 0xb9800000, v67
	v_mul_f32_e32 v66, v186, v186
	v_pk_mov_b32 v[134:135], v[132:133], v[130:131] op_sel:[1,0]
	v_mov_b32_e32 v133, v131
	v_fmac_f32_e32 v68, 0xb9800000, v182
	v_pk_fma_f32 v[66:67], v[186:187], v[186:187], v[66:67] op_sel_hi:[1,1,0]
	v_pk_add_f32 v[130:131], v[134:135], v[132:133]
	v_fmamk_f32 v69, v182, 0xb9800000, v69
	v_mul_f32_e32 v66, v68, v68
	v_pk_add_f32 v[84:85], v[84:85], v[84:85] op_sel_hi:[0,1]
	v_pk_add_f32 v[130:131], v[130:131], v[130:131] op_sel_hi:[0,1]
	v_pk_fma_f32 v[132:133], v[68:69], v[68:69], v[66:67] op_sel_hi:[1,1,0]
	v_fmamk_f32 v139, v182, 0xb9800000, v93
	v_fmamk_f32 v138, v182, 0xb9800000, v92
	v_fmamk_f32 v91, v182, 0xb9800000, v91
	v_fmac_f32_e32 v90, 0xb9800000, v182
	v_mul_f32_e32 v66, v90, v90
	v_mul_f32_e32 v132, v91, v91
	v_mul_f32_e32 v130, v138, v138
	v_mul_f32_e32 v84, v139, v139
	v_pk_add_f32 v[66:67], v[66:67], v[132:133]
	v_pk_add_f32 v[84:85], v[130:131], v[84:85]
	v_fmamk_f32 v135, v182, 0xb9800000, v95
	v_pk_add_f32 v[66:67], v[66:67], v[84:85]
	v_fmamk_f32 v134, v182, 0xb9800000, v94
	v_fmamk_f32 v97, v182, 0xb9800000, v97
	v_fmac_f32_e32 v96, 0xb9800000, v182
	v_pk_add_f32 v[84:85], v[66:67], v[66:67] op_sel_hi:[0,1]
	v_pk_mul_f32 v[66:67], v[96:97], v[96:97]
	v_pk_mul_f32 v[92:93], v[134:135], v[134:135]
	v_fmac_f32_e32 v100, 0xb9800000, v182
	v_pk_mov_b32 v[94:95], v[92:93], v[66:67] op_sel:[1,0]
	v_mov_b32_e32 v93, v67
	v_pk_add_f32 v[66:67], v[94:95], v[92:93]
	v_fmamk_f32 v101, v182, 0xb9800000, v101
	v_pk_add_f32 v[92:93], v[66:67], v[66:67] op_sel_hi:[0,1]
	v_fmamk_f32 v66, v182, 0xb9800000, v98
	v_fmamk_f32 v67, v182, 0xb9800000, v99
	v_mul_f32_e32 v84, v66, v66
	v_pk_fma_f32 v[94:95], v[66:67], v[66:67], v[84:85] op_sel_hi:[1,1,0]
	v_mul_f32_e32 v84, v100, v100
	v_pk_fma_f32 v[98:99], v[100:101], v[100:101], v[84:85] op_sel_hi:[1,1,0]
	v_fmamk_f32 v131, v182, 0xb9800000, v113
	v_fmamk_f32 v130, v182, 0xb9800000, v112
	v_fmamk_f32 v111, v182, 0xb9800000, v111
	v_fmac_f32_e32 v110, 0xb9800000, v182
	v_mul_f32_e32 v94, v110, v110
	v_mul_f32_e32 v98, v111, v111
	v_mul_f32_e32 v92, v130, v130
	v_mul_f32_e32 v84, v131, v131
	v_pk_add_f32 v[94:95], v[94:95], v[98:99]
	v_pk_add_f32 v[84:85], v[92:93], v[84:85]
	v_fmamk_f32 v107, v182, 0xb9800000, v107
	v_pk_add_f32 v[84:85], v[94:95], v[84:85]
	v_fmamk_f32 v106, v182, 0xb9800000, v106
	v_fmamk_f32 v109, v182, 0xb9800000, v109
	v_fmac_f32_e32 v108, 0xb9800000, v182
	v_pk_add_f32 v[84:85], v[84:85], v[84:85] op_sel_hi:[0,1]
	v_pk_mul_f32 v[92:93], v[108:109], v[108:109]
	v_pk_mul_f32 v[94:95], v[106:107], v[106:107]
	v_fmamk_f32 v102, v182, 0xb9800000, v102
	v_pk_mov_b32 v[98:99], v[94:95], v[92:93] op_sel:[1,0]
	v_mov_b32_e32 v95, v93
	v_fmamk_f32 v103, v182, 0xb9800000, v103
	v_fmac_f32_e32 v104, 0xb9800000, v182
	v_mul_f32_e32 v84, v102, v102
	v_pk_add_f32 v[92:93], v[98:99], v[94:95]
	v_fmamk_f32 v105, v182, 0xb9800000, v105
	v_pk_fma_f32 v[94:95], v[102:103], v[102:103], v[84:85] op_sel_hi:[1,1,0]
	v_mul_f32_e32 v84, v104, v104
	v_pk_add_f32 v[92:93], v[92:93], v[92:93] op_sel_hi:[0,1]
	v_pk_fma_f32 v[98:99], v[104:105], v[104:105], v[84:85] op_sel_hi:[1,1,0]
	v_fmamk_f32 v133, v182, 0xb9800000, v125
	v_fmamk_f32 v132, v182, 0xb9800000, v124
	v_fmamk_f32 v123, v182, 0xb9800000, v123
	v_fmac_f32_e32 v122, 0xb9800000, v182
	v_mul_f32_e32 v94, v122, v122
	v_mul_f32_e32 v98, v123, v123
	v_mul_f32_e32 v92, v132, v132
	v_mul_f32_e32 v84, v133, v133
	v_pk_add_f32 v[94:95], v[94:95], v[98:99]
	v_pk_add_f32 v[84:85], v[92:93], v[84:85]
	v_fmamk_f32 v137, v182, 0xb9800000, v115
	v_pk_add_f32 v[84:85], v[94:95], v[84:85]
	v_fmamk_f32 v136, v182, 0xb9800000, v114
	v_fmamk_f32 v117, v182, 0xb9800000, v117
	v_fmac_f32_e32 v116, 0xb9800000, v182
	v_pk_add_f32 v[84:85], v[84:85], v[84:85] op_sel_hi:[0,1]
	v_pk_mul_f32 v[92:93], v[116:117], v[116:117]
	v_pk_mul_f32 v[94:95], v[136:137], v[136:137]
	v_fmamk_f32 v124, v182, 0xb9800000, v118
	v_pk_mov_b32 v[98:99], v[94:95], v[92:93] op_sel:[1,0]
	v_mov_b32_e32 v95, v93
	v_fmamk_f32 v125, v182, 0xb9800000, v119
	v_fmac_f32_e32 v120, 0xb9800000, v182
	v_mul_f32_e32 v84, v124, v124
	v_pk_add_f32 v[92:93], v[98:99], v[94:95]
	v_fmamk_f32 v121, v182, 0xb9800000, v121
	v_pk_fma_f32 v[94:95], v[124:125], v[124:125], v[84:85] op_sel_hi:[1,1,0]
	v_mul_f32_e32 v84, v120, v120
	v_pk_add_f32 v[92:93], v[92:93], v[92:93] op_sel_hi:[0,1]
	v_pk_fma_f32 v[98:99], v[120:121], v[120:121], v[84:85] op_sel_hi:[1,1,0]
	v_fmamk_f32 v119, v182, 0xb9800000, v129
	v_fmamk_f32 v118, v182, 0xb9800000, v128
	v_fmamk_f32 v127, v182, 0xb9800000, v127
	v_fmac_f32_e32 v126, 0xb9800000, v182
	v_mul_f32_e32 v94, v126, v126
	v_mul_f32_e32 v98, v127, v127
	v_mul_f32_e32 v92, v118, v118
	v_mul_f32_e32 v84, v119, v119
	v_pk_add_f32 v[94:95], v[94:95], v[98:99]
	v_pk_add_f32 v[84:85], v[92:93], v[84:85]
	v_lshl_add_u64 v[182:183], s[40:41], 0, v[180:181]
	v_pk_add_f32 v[84:85], v[94:95], v[84:85]
	s_nop 0
	v_add_f32_e32 v84, v84, v85
	ds_bpermute_b32 v85, v185, v84
	s_waitcnt lgkmcnt(0)
	v_add_f32_e32 v84, v84, v85
	ds_bpermute_b32 v85, v190, v84
	s_waitcnt lgkmcnt(0)
	v_add_f32_e32 v84, v84, v85
	ds_bpermute_b32 v85, v191, v84
	s_waitcnt lgkmcnt(0)
	v_add_f32_e32 v84, v84, v85
	ds_bpermute_b32 v85, v192, v84
	s_waitcnt lgkmcnt(0)
	v_add_f32_e32 v84, v84, v85
	ds_bpermute_b32 v85, v193, v84
	s_waitcnt lgkmcnt(0)
	v_add_f32_e32 v84, v84, v85
	ds_bpermute_b32 v85, v194, v84
	s_waitcnt lgkmcnt(0)
	v_add_f32_e32 v84, v84, v85
	v_fmamk_f32 v84, v84, 0x39800000, v179
	v_mul_f32_e32 v85, 0x4f800000, v84
	v_cmp_gt_f32_e32 vcc, s48, v84
	s_nop 1
	v_cndmask_b32_e32 v84, v84, v85, vcc
	v_sqrt_f32_e32 v85, v84
	s_nop 0
	v_add_u32_e32 v92, -1, v85
	v_fma_f32 v93, -v92, v85, v84
	v_cmp_ge_f32_e64 s[0:1], 0, v93
	v_add_u32_e32 v93, 1, v85
	s_nop 0
	v_cndmask_b32_e64 v92, v85, v92, s[0:1]
	v_fma_f32 v85, -v93, v85, v84
	v_cmp_lt_f32_e64 s[0:1], 0, v85
	s_nop 1
	v_cndmask_b32_e64 v85, v92, v93, s[0:1]
	v_mul_f32_e32 v92, 0x37800000, v85
	v_cndmask_b32_e32 v85, v85, v92, vcc
	v_cmp_class_f32_e32 vcc, v84, v237
	s_nop 1
	v_cndmask_b32_e32 v84, v85, v84, vcc
	v_div_scale_f32 v85, s[0:1], v84, v84, 1.0
	v_rcp_f32_e32 v92, v85
	s_nop 0
	v_fma_f32 v93, -v85, v92, 1.0
	v_fmac_f32_e32 v92, v93, v92
	v_div_scale_f32 v93, vcc, 1.0, v84, 1.0
	v_mul_f32_e32 v94, v93, v92
	v_fma_f32 v95, -v85, v94, v93
	v_fmac_f32_e32 v94, v95, v92
	v_fma_f32 v85, -v85, v94, v93
	v_div_fmas_f32 v85, v85, v92, v94
	ds_read_b128 v[92:95], v236
	ds_read_b128 v[112:115], v236 offset:16384
	v_div_fixup_f32 v184, v85, v84, 1.0
	ds_read_b128 v[196:199], v236 offset:17408
	ds_read_b128 v[200:203], v236 offset:1024
	v_pk_mul_f32 v[88:89], v[88:89], v[184:185] op_sel_hi:[1,0]
	v_pk_mul_f32 v[84:85], v[86:87], v[184:185] op_sel_hi:[1,0]
	s_waitcnt lgkmcnt(2)
	v_pk_fma_f32 v[86:87], v[94:95], v[88:89], v[114:115]
	v_pk_fma_f32 v[84:85], v[92:93], v[84:85], v[112:113]
	v_mov_b32_e32 v93, v87
	v_pk_mov_b32 v[88:89], v[84:85], v[86:87] op_sel:[1,0]
	v_mov_b32_e32 v92, v84
	v_pk_add_f32 v[88:89], v[88:89], v[92:93]
	v_pk_mul_f32 v[80:81], v[80:81], v[184:185] op_sel_hi:[1,0]
	v_pk_mul_f32 v[92:93], v[188:189], v[184:185] op_sel_hi:[1,0]
	s_waitcnt lgkmcnt(0)
	v_pk_fma_f32 v[94:95], v[202:203], v[80:81], v[198:199]
	v_pk_fma_f32 v[92:93], v[200:201], v[92:93], v[196:197]
	global_store_dwordx4 v180, v[84:87], s[40:41] sc1 nt
	global_store_dwordx4 v180, v[92:95], s[40:41] offset:1024 sc1 nt
	ds_read_b128 v[112:115], v236 offset:18432
	ds_read_b128 v[196:199], v236 offset:2048
	ds_read_b128 v[200:203], v236 offset:19456
	ds_read_b128 v[204:207], v236 offset:3072
	v_pk_mov_b32 v[80:81], v[92:93], v[94:95] op_sel:[1,0]
	v_mov_b32_e32 v98, v92
	v_mov_b32_e32 v99, v95
	v_pk_add_f32 v[80:81], v[80:81], v[98:99]
	v_pk_mul_f32 v[76:77], v[76:77], v[184:185] op_sel_hi:[1,0]
	v_pk_mul_f32 v[78:79], v[78:79], v[184:185] op_sel_hi:[1,0]
	v_pk_mul_f32 v[82:83], v[82:83], v[184:185] op_sel_hi:[1,0]
	v_pk_mul_f32 v[74:75], v[74:75], v[184:185] op_sel_hi:[1,0]
	v_pk_add_f32 v[98:99], v[80:81], v[80:81] op_sel_hi:[0,1]
	s_waitcnt lgkmcnt(2)
	v_pk_fma_f32 v[78:79], v[196:197], v[78:79], v[112:113]
	v_pk_fma_f32 v[80:81], v[198:199], v[76:77], v[114:115]
	s_waitcnt lgkmcnt(0)
	v_pk_fma_f32 v[76:77], v[206:207], v[74:75], v[202:203]
	v_pk_fma_f32 v[74:75], v[204:205], v[82:83], v[200:201]
	global_store_dwordx4 v180, v[78:81], s[40:41] offset:2048 sc1 nt
	global_store_dwordx4 v180, v[74:77], s[40:41] offset:3072 sc1 nt
	v_add_f32_e32 v113, v78, v79
	v_add_f32_e32 v115, v80, v81
	v_mov_b32_e32 v112, v74
	v_mov_b32_e32 v114, v75
	v_pk_add_f32 v[82:83], v[112:113], v[114:115]
	ds_read_b128 v[112:115], v236 offset:4096
	ds_read_b128 v[196:199], v236 offset:20480
	v_add_f32_e32 v88, v88, v89
	v_add_f32_e32 v89, 0, v88
	v_mov_b32_e32 v98, v76
	v_mov_b32_e32 v88, v77
	v_pk_mul_f32 v[70:71], v[70:71], v[184:185] op_sel_hi:[1,0]
	v_pk_mul_f32 v[72:73], v[72:73], v[184:185] op_sel_hi:[1,0]
	ds_read_b128 v[200:203], v236 offset:21504
	ds_read_b128 v[204:207], v236 offset:5120
	v_pk_add_f32 v[88:89], v[98:99], v[88:89]
	s_waitcnt lgkmcnt(2)
	v_pk_fma_f32 v[72:73], v[114:115], v[72:73], v[198:199]
	v_pk_fma_f32 v[70:71], v[112:113], v[70:71], v[196:197]
	v_pk_add_f32 v[82:83], v[82:83], v[88:89]
	v_add_co_u32_e32 v128, vcc, s46, v182
	v_pk_mov_b32 v[88:89], v[70:71], v[72:73] op_sel:[1,0]
	v_mov_b32_e32 v98, v70
	v_mov_b32_e32 v99, v73
	v_addc_co_u32_e32 v129, vcc, 0, v183, vcc
	v_pk_add_f32 v[88:89], v[88:89], v[98:99]
	v_add_co_u32_e32 v208, vcc, s45, v182
	v_pk_add_f32 v[98:99], v[88:89], v[88:89] op_sel_hi:[0,1]
	v_pk_mul_f32 v[88:89], v[186:187], v[184:185] op_sel_hi:[1,0]
	v_pk_mul_f32 v[68:69], v[68:69], v[184:185] op_sel_hi:[1,0]
	v_addc_co_u32_e32 v209, vcc, 0, v183, vcc
	s_waitcnt lgkmcnt(0)
	v_pk_fma_f32 v[114:115], v[206:207], v[68:69], v[202:203]
	v_pk_fma_f32 v[112:113], v[204:205], v[88:89], v[200:201]
	global_store_dwordx4 v[208:209], v[70:73], off offset:-4096 sc1 nt
	global_store_dwordx4 v[128:129], v[112:115], off offset:1024 sc1 nt
	ds_read_b128 v[186:189], v236 offset:22528
	ds_read_b128 v[196:199], v236 offset:6144
	v_pk_mul_f32 v[88:89], v[90:91], v[184:185] op_sel_hi:[1,0]
	v_pk_mul_f32 v[90:91], v[138:139], v[184:185] op_sel_hi:[1,0]
	v_pk_add_f32 v[82:83], v[82:83], v[82:83] op_sel_hi:[0,1]
	ds_read_b128 v[200:203], v236 offset:23552
	ds_read_b128 v[204:207], v236 offset:7168
	s_waitcnt lgkmcnt(2)
	v_pk_fma_f32 v[90:91], v[198:199], v[90:91], v[188:189]
	v_pk_fma_f32 v[88:89], v[196:197], v[88:89], v[186:187]
	v_add_f32_e32 v69, v112, v113
	v_add_f32_e32 v211, v114, v115
	v_mov_b32_e32 v68, v88
	v_mov_b32_e32 v210, v89
	v_mov_b32_e32 v98, v90
	v_mov_b32_e32 v82, v91
	v_pk_add_f32 v[68:69], v[68:69], v[210:211]
	v_pk_add_f32 v[82:83], v[98:99], v[82:83]
	v_pk_mul_f32 v[96:97], v[96:97], v[184:185] op_sel_hi:[1,0]
	v_pk_add_f32 v[68:69], v[68:69], v[82:83]
	s_waitcnt lgkmcnt(0)
	v_pk_fma_f32 v[98:99], v[206:207], v[96:97], v[202:203]
	v_pk_add_f32 v[82:83], v[68:69], v[68:69] op_sel_hi:[0,1]
	v_pk_mul_f32 v[68:69], v[134:135], v[184:185] op_sel_hi:[1,0]
	global_store_dwordx4 v[128:129], v[88:91], off offset:2048 sc1 nt
	v_pk_fma_f32 v[96:97], v[204:205], v[68:69], v[200:201]
	global_store_dwordx4 v[128:129], v[96:99], off offset:3072 sc1 nt
	ds_read_b128 v[186:189], v236 offset:8192
	ds_read_b128 v[196:199], v236 offset:24576
	ds_read_b128 v[200:203], v236 offset:25600
	ds_read_b128 v[204:207], v236 offset:9216
	v_pk_mov_b32 v[68:69], v[96:97], v[98:99] op_sel:[1,0]
	v_mov_b32_e32 v128, v96
	v_mov_b32_e32 v129, v99
	v_pk_add_f32 v[68:69], v[68:69], v[128:129]
	v_pk_mul_f32 v[66:67], v[66:67], v[184:185] op_sel_hi:[1,0]
	v_pk_add_f32 v[134:135], v[68:69], v[68:69] op_sel_hi:[0,1]
	v_pk_mul_f32 v[68:69], v[100:101], v[184:185] op_sel_hi:[1,0]
	v_pk_mul_f32 v[110:111], v[110:111], v[184:185] op_sel_hi:[1,0]
	v_pk_mul_f32 v[128:129], v[130:131], v[184:185] op_sel_hi:[1,0]
	s_waitcnt lgkmcnt(2)
	v_pk_fma_f32 v[68:69], v[188:189], v[68:69], v[198:199]
	v_pk_fma_f32 v[66:67], v[186:187], v[66:67], v[196:197]
	s_waitcnt lgkmcnt(0)
	v_pk_fma_f32 v[130:131], v[206:207], v[128:129], v[202:203]
	v_pk_fma_f32 v[128:129], v[204:205], v[110:111], v[200:201]
	global_store_dwordx4 v[208:209], v[66:69], off sc1 nt
	global_store_dwordx4 v[208:209], v[128:131], off offset:1024 sc1 nt
	ds_read_b128 v[186:189], v236 offset:26624
	ds_read_b128 v[196:199], v236 offset:10240
	v_add_f32_e32 v101, v66, v67
	v_add_f32_e32 v139, v68, v69
	v_mov_b32_e32 v100, v128
	v_mov_b32_e32 v138, v129
	v_mov_b32_e32 v134, v130
	v_mov_b32_e32 v82, v131
	v_pk_add_f32 v[100:101], v[100:101], v[138:139]
	v_pk_add_f32 v[82:83], v[134:135], v[82:83]
	ds_read_b128 v[200:203], v236 offset:27648
	ds_read_b128 v[204:207], v236 offset:11264
	v_pk_add_f32 v[82:83], v[100:101], v[82:83]
	v_pk_mul_f32 v[100:101], v[106:107], v[184:185] op_sel_hi:[1,0]
	v_pk_mul_f32 v[106:107], v[108:109], v[184:185] op_sel_hi:[1,0]
	v_pk_mul_f32 v[122:123], v[122:123], v[184:185] op_sel_hi:[1,0]
	s_waitcnt lgkmcnt(2)
	v_pk_fma_f32 v[108:109], v[106:107], v[198:199], v[188:189]
	v_pk_fma_f32 v[106:107], v[100:101], v[196:197], v[186:187]
	v_mov_b32_e32 v111, v109
	v_pk_mov_b32 v[100:101], v[106:107], v[108:109] op_sel:[1,0]
	v_mov_b32_e32 v110, v106
	v_pk_add_f32 v[100:101], v[100:101], v[110:111]
	global_store_dwordx4 v[208:209], v[106:109], off offset:2048 sc1 nt
	v_pk_add_f32 v[110:111], v[100:101], v[100:101] op_sel_hi:[0,1]
	v_pk_mul_f32 v[100:101], v[102:103], v[184:185] op_sel_hi:[1,0]
	v_pk_mul_f32 v[102:103], v[104:105], v[184:185] op_sel_hi:[1,0]
	s_waitcnt lgkmcnt(0)
	v_pk_fma_f32 v[100:101], v[100:101], v[204:205], v[200:201]
	v_pk_fma_f32 v[102:103], v[102:103], v[206:207], v[202:203]
	global_store_dwordx4 v[208:209], v[100:103], off offset:3072 sc1 nt
	ds_read_b128 v[186:189], v236 offset:12288
	ds_read_b128 v[196:199], v236 offset:28672
	v_pk_mul_f32 v[132:133], v[132:133], v[184:185] op_sel_hi:[1,0]
	ds_read_b128 v[200:203], v236 offset:29696
	ds_read_b128 v[204:207], v236 offset:13312
	v_pk_add_f32 v[82:83], v[82:83], v[82:83] op_sel_hi:[0,1]
	v_add_f32_e32 v105, v100, v101
	s_waitcnt lgkmcnt(2)
	v_pk_fma_f32 v[134:135], v[132:133], v[188:189], v[198:199]
	v_pk_fma_f32 v[132:133], v[122:123], v[186:187], v[196:197]
	v_add_f32_e32 v139, v102, v103
	v_mov_b32_e32 v104, v132
	v_mov_b32_e32 v138, v133
	v_mov_b32_e32 v110, v134
	v_mov_b32_e32 v82, v135
	v_pk_add_f32 v[104:105], v[104:105], v[138:139]
	v_pk_add_f32 v[82:83], v[110:111], v[82:83]
	v_pk_mul_f32 v[110:111], v[116:117], v[184:185] op_sel_hi:[1,0]
	v_pk_add_f32 v[82:83], v[104:105], v[82:83]
	v_pk_mul_f32 v[104:105], v[136:137], v[184:185] op_sel_hi:[1,0]
	ds_read_b128 v[186:189], v236 offset:30720
	ds_read_b128 v[196:199], v236 offset:14336
	s_waitcnt lgkmcnt(2)
	v_pk_fma_f32 v[138:139], v[110:111], v[206:207], v[202:203]
	v_pk_fma_f32 v[136:137], v[104:105], v[204:205], v[200:201]
	ds_read_b128 v[200:203], v236 offset:31744
	ds_read_b128 v[204:207], v236 offset:15360
	v_pk_mov_b32 v[104:105], v[136:137], v[138:139] op_sel:[1,0]
	v_mov_b32_e32 v110, v136
	v_mov_b32_e32 v111, v139
	v_pk_mul_f32 v[116:117], v[120:121], v[184:185] op_sel_hi:[1,0]
	v_pk_add_f32 v[104:105], v[104:105], v[110:111]
	v_pk_mul_f32 v[110:111], v[124:125], v[184:185] op_sel_hi:[1,0]
	s_waitcnt lgkmcnt(2)
	v_pk_fma_f32 v[122:123], v[116:117], v[198:199], v[188:189]
	v_pk_mul_f32 v[116:117], v[126:127], v[184:185] op_sel_hi:[1,0]
	v_pk_mul_f32 v[118:119], v[118:119], v[184:185] op_sel_hi:[1,0]
	v_pk_add_f32 v[82:83], v[82:83], v[82:83] op_sel:[0,1] op_sel_hi:[1,0]
	v_pk_add_f32 v[104:105], v[104:105], v[104:105] op_sel:[0,1] op_sel_hi:[1,0]
	v_pk_fma_f32 v[120:121], v[110:111], v[196:197], v[186:187]
	s_waitcnt lgkmcnt(0)
	v_pk_fma_f32 v[118:119], v[118:119], v[206:207], v[202:203]
	v_pk_fma_f32 v[116:117], v[116:117], v[204:205], v[200:201]
	v_add_f32_e32 v110, v120, v121
	v_add_f32_e32 v124, v122, v123
	v_mov_b32_e32 v105, v116
	v_mov_b32_e32 v83, v117
	v_mov_b32_e32 v111, v118
	v_mov_b32_e32 v125, v119
	v_pk_add_f32 v[82:83], v[104:105], v[82:83]
	v_pk_add_f32 v[104:105], v[110:111], v[124:125]
	s_nop 0
	v_pk_add_f32 v[82:83], v[82:83], v[104:105]
	s_nop 0
	v_add_f32_e32 v82, v82, v83
	ds_bpermute_b32 v83, v185, v82
	s_waitcnt lgkmcnt(0)
	v_add_f32_e32 v82, v82, v83
	ds_bpermute_b32 v83, v190, v82
	s_waitcnt lgkmcnt(0)
	v_add_f32_e32 v82, v82, v83
	ds_bpermute_b32 v83, v191, v82
	s_waitcnt lgkmcnt(0)
	v_add_f32_e32 v82, v82, v83
	ds_bpermute_b32 v83, v192, v82
	s_waitcnt lgkmcnt(0)
	v_add_f32_e32 v104, v82, v83
	ds_bpermute_b32 v105, v193, v104
	v_add_co_u32_e32 v82, vcc, s47, v182
	s_waitcnt lgkmcnt(0)
	v_add_f32_e32 v104, v104, v105
	ds_bpermute_b32 v105, v194, v104
	v_addc_co_u32_e32 v83, vcc, 0, v183, vcc
	global_store_dwordx4 v[82:83], v[132:135], off sc1 nt
	global_store_dwordx4 v[82:83], v[136:139], off offset:1024 sc1 nt
	global_store_dwordx4 v[82:83], v[120:123], off offset:2048 sc1 nt
	global_store_dwordx4 v[82:83], v[116:119], off offset:3072 sc1 nt
	s_waitcnt lgkmcnt(0)
	v_add_f32_e32 v126, v104, v105
	v_fmamk_f32 v85, v126, 0xb9800000, v85
	v_fmac_f32_e32 v84, 0xb9800000, v126
	v_fmamk_f32 v87, v126, 0xb9800000, v87
	v_fmac_f32_e32 v86, 0xb9800000, v126
	v_pk_mul_f32 v[82:83], v[86:87], v[86:87]
	v_pk_mul_f32 v[104:105], v[84:85], v[84:85]
	v_fmamk_f32 v93, v126, 0xb9800000, v93
	v_pk_mov_b32 v[110:111], v[104:105], v[82:83] op_sel:[1,0]
	v_mov_b32_e32 v105, v83
	v_pk_add_f32 v[82:83], v[110:111], v[104:105]
	v_fmac_f32_e32 v92, 0xb9800000, v126
	v_fmamk_f32 v95, v126, 0xb9800000, v95
	v_fmac_f32_e32 v94, 0xb9800000, v126
	v_pk_add_f32 v[82:83], v[82:83], v[82:83] op_sel_hi:[0,1]
	v_pk_mul_f32 v[104:105], v[94:95], v[94:95]
	v_pk_mul_f32 v[110:111], v[92:93], v[92:93]
	v_fmac_f32_e32 v78, 0xb9800000, v126
	v_pk_mov_b32 v[124:125], v[110:111], v[104:105] op_sel:[1,0]
	v_mov_b32_e32 v111, v105
	v_fmamk_f32 v79, v126, 0xb9800000, v79
	v_fmac_f32_e32 v80, 0xb9800000, v126
	v_mul_f32_e32 v82, v78, v78
	v_pk_add_f32 v[104:105], v[124:125], v[110:111]
	v_fmamk_f32 v81, v126, 0xb9800000, v81
	v_pk_fma_f32 v[110:111], v[78:79], v[78:79], v[82:83] op_sel_hi:[1,1,0]
	v_mul_f32_e32 v82, v80, v80
	v_pk_add_f32 v[104:105], v[104:105], v[104:105] op_sel_hi:[0,1]
	v_pk_fma_f32 v[124:125], v[80:81], v[80:81], v[82:83] op_sel_hi:[1,1,0]
	v_fmamk_f32 v77, v126, 0xb9800000, v77
	v_fmac_f32_e32 v76, 0xb9800000, v126
	v_fmamk_f32 v75, v126, 0xb9800000, v75
	v_fmac_f32_e32 v74, 0xb9800000, v126
	v_mul_f32_e32 v110, v74, v74
	v_mul_f32_e32 v124, v75, v75
	v_mul_f32_e32 v82, v76, v76
	v_mul_f32_e32 v104, v77, v77
	v_pk_add_f32 v[110:111], v[110:111], v[124:125]
	v_pk_add_f32 v[82:83], v[82:83], v[104:105]
	v_fmamk_f32 v71, v126, 0xb9800000, v71
	v_pk_add_f32 v[82:83], v[110:111], v[82:83]
	v_fmac_f32_e32 v70, 0xb9800000, v126
	v_fmamk_f32 v73, v126, 0xb9800000, v73
	v_fmac_f32_e32 v72, 0xb9800000, v126
	v_pk_add_f32 v[82:83], v[82:83], v[82:83] op_sel_hi:[0,1]
	v_pk_mul_f32 v[104:105], v[72:73], v[72:73]
	v_pk_mul_f32 v[110:111], v[70:71], v[70:71]
	v_fmac_f32_e32 v112, 0xb9800000, v126
	v_pk_mov_b32 v[124:125], v[110:111], v[104:105] op_sel:[1,0]
	v_mov_b32_e32 v111, v105
	v_fmamk_f32 v113, v126, 0xb9800000, v113
	v_fmac_f32_e32 v114, 0xb9800000, v126
	v_mul_f32_e32 v82, v112, v112
	v_pk_add_f32 v[104:105], v[124:125], v[110:111]
	v_fmamk_f32 v115, v126, 0xb9800000, v115
	v_pk_fma_f32 v[110:111], v[112:113], v[112:113], v[82:83] op_sel_hi:[1,1,0]
	v_mul_f32_e32 v82, v114, v114
	v_pk_add_f32 v[104:105], v[104:105], v[104:105] op_sel_hi:[0,1]
	v_pk_fma_f32 v[124:125], v[114:115], v[114:115], v[82:83] op_sel_hi:[1,1,0]
	v_fmamk_f32 v91, v126, 0xb9800000, v91
	v_fmac_f32_e32 v90, 0xb9800000, v126
	v_fmamk_f32 v89, v126, 0xb9800000, v89
	v_fmac_f32_e32 v88, 0xb9800000, v126
	v_mul_f32_e32 v110, v88, v88
	v_mul_f32_e32 v124, v89, v89
	v_mul_f32_e32 v104, v90, v90
	v_mul_f32_e32 v82, v91, v91
	v_pk_add_f32 v[110:111], v[110:111], v[124:125]
	v_pk_add_f32 v[82:83], v[104:105], v[82:83]
	v_fmamk_f32 v97, v126, 0xb9800000, v97
	v_pk_add_f32 v[82:83], v[110:111], v[82:83]
	v_fmac_f32_e32 v96, 0xb9800000, v126
	v_fmamk_f32 v99, v126, 0xb9800000, v99
	v_fmac_f32_e32 v98, 0xb9800000, v126
	v_pk_add_f32 v[82:83], v[82:83], v[82:83] op_sel_hi:[0,1]
	v_pk_mul_f32 v[104:105], v[98:99], v[98:99]
	v_pk_mul_f32 v[110:111], v[96:97], v[96:97]
	v_fmac_f32_e32 v66, 0xb9800000, v126
	v_pk_mov_b32 v[124:125], v[110:111], v[104:105] op_sel:[1,0]
	v_mov_b32_e32 v111, v105
	v_fmamk_f32 v67, v126, 0xb9800000, v67
	v_fmac_f32_e32 v68, 0xb9800000, v126
	v_mul_f32_e32 v82, v66, v66
	v_pk_add_f32 v[104:105], v[124:125], v[110:111]
	v_fmamk_f32 v69, v126, 0xb9800000, v69
	v_pk_fma_f32 v[110:111], v[66:67], v[66:67], v[82:83] op_sel_hi:[1,1,0]
	v_mul_f32_e32 v82, v68, v68
	v_pk_add_f32 v[104:105], v[104:105], v[104:105] op_sel_hi:[0,1]
	v_pk_fma_f32 v[124:125], v[68:69], v[68:69], v[82:83] op_sel_hi:[1,1,0]
	v_fmamk_f32 v131, v126, 0xb9800000, v131
	v_fmac_f32_e32 v130, 0xb9800000, v126
	v_fmamk_f32 v129, v126, 0xb9800000, v129
	v_fmac_f32_e32 v128, 0xb9800000, v126
	v_mul_f32_e32 v110, v128, v128
	v_mul_f32_e32 v124, v129, v129
	v_mul_f32_e32 v104, v130, v130
	v_mul_f32_e32 v82, v131, v131
	v_pk_add_f32 v[110:111], v[110:111], v[124:125]
	v_pk_add_f32 v[82:83], v[104:105], v[82:83]
	v_fmamk_f32 v107, v126, 0xb9800000, v107
	v_pk_add_f32 v[82:83], v[110:111], v[82:83]
	v_fmac_f32_e32 v106, 0xb9800000, v126
	v_fmamk_f32 v109, v126, 0xb9800000, v109
	v_fmac_f32_e32 v108, 0xb9800000, v126
	v_pk_add_f32 v[82:83], v[82:83], v[82:83] op_sel_hi:[0,1]
	v_pk_mul_f32 v[104:105], v[108:109], v[108:109]
	v_pk_mul_f32 v[110:111], v[106:107], v[106:107]
	v_fmac_f32_e32 v100, 0xb9800000, v126
	v_pk_mov_b32 v[124:125], v[110:111], v[104:105] op_sel:[1,0]
	v_mov_b32_e32 v111, v105
	v_fmamk_f32 v101, v126, 0xb9800000, v101
	v_fmac_f32_e32 v102, 0xb9800000, v126
	v_mul_f32_e32 v82, v100, v100
	v_pk_add_f32 v[104:105], v[124:125], v[110:111]
	v_fmamk_f32 v103, v126, 0xb9800000, v103
	v_pk_fma_f32 v[110:111], v[100:101], v[100:101], v[82:83] op_sel_hi:[1,1,0]
	v_mul_f32_e32 v82, v102, v102
	v_pk_add_f32 v[104:105], v[104:105], v[104:105] op_sel_hi:[0,1]
	v_pk_fma_f32 v[124:125], v[102:103], v[102:103], v[82:83] op_sel_hi:[1,1,0]
	v_fmamk_f32 v135, v126, 0xb9800000, v135
	v_fmac_f32_e32 v134, 0xb9800000, v126
	v_fmamk_f32 v133, v126, 0xb9800000, v133
	v_fmac_f32_e32 v132, 0xb9800000, v126
	v_mul_f32_e32 v110, v132, v132
	v_mul_f32_e32 v124, v133, v133
	v_mul_f32_e32 v104, v134, v134
	v_mul_f32_e32 v82, v135, v135
	v_pk_add_f32 v[110:111], v[110:111], v[124:125]
	v_pk_add_f32 v[82:83], v[104:105], v[82:83]
	v_fmamk_f32 v137, v126, 0xb9800000, v137
	v_pk_add_f32 v[82:83], v[110:111], v[82:83]
	v_fmac_f32_e32 v136, 0xb9800000, v126
	v_fmamk_f32 v139, v126, 0xb9800000, v139
	v_fmac_f32_e32 v138, 0xb9800000, v126
	v_pk_add_f32 v[82:83], v[82:83], v[82:83] op_sel_hi:[0,1]
	v_pk_mul_f32 v[104:105], v[138:139], v[138:139]
	v_pk_mul_f32 v[110:111], v[136:137], v[136:137]
	v_fmac_f32_e32 v120, 0xb9800000, v126
	v_pk_mov_b32 v[124:125], v[110:111], v[104:105] op_sel:[1,0]
	v_mov_b32_e32 v111, v105
	v_fmamk_f32 v121, v126, 0xb9800000, v121
	v_fmac_f32_e32 v122, 0xb9800000, v126
	v_mul_f32_e32 v82, v120, v120
	v_pk_add_f32 v[104:105], v[124:125], v[110:111]
	v_fmamk_f32 v123, v126, 0xb9800000, v123
	v_pk_fma_f32 v[110:111], v[120:121], v[120:121], v[82:83] op_sel_hi:[1,1,0]
	v_mul_f32_e32 v82, v122, v122
	v_pk_add_f32 v[104:105], v[104:105], v[104:105] op_sel_hi:[0,1]
	v_pk_fma_f32 v[124:125], v[122:123], v[122:123], v[82:83] op_sel_hi:[1,1,0]
	v_fmamk_f32 v119, v126, 0xb9800000, v119
	v_fmac_f32_e32 v118, 0xb9800000, v126
	v_fmamk_f32 v117, v126, 0xb9800000, v117
	v_fmac_f32_e32 v116, 0xb9800000, v126
	v_mul_f32_e32 v110, v116, v116
	v_mul_f32_e32 v124, v117, v117
	v_mul_f32_e32 v104, v118, v118
	v_mul_f32_e32 v82, v119, v119
	v_pk_add_f32 v[110:111], v[110:111], v[124:125]
	v_pk_add_f32 v[82:83], v[104:105], v[82:83]
	s_nop 0
	v_pk_add_f32 v[82:83], v[110:111], v[82:83]
	s_nop 0
	v_add_f32_e32 v82, v82, v83
	ds_bpermute_b32 v83, v185, v82
	s_waitcnt lgkmcnt(0)
	v_add_f32_e32 v82, v82, v83
	ds_bpermute_b32 v83, v190, v82
	s_waitcnt lgkmcnt(0)
	v_add_f32_e32 v82, v82, v83
	ds_bpermute_b32 v83, v191, v82
	s_waitcnt lgkmcnt(0)
	v_add_f32_e32 v82, v82, v83
	ds_bpermute_b32 v83, v192, v82
	s_waitcnt lgkmcnt(0)
	v_add_f32_e32 v82, v82, v83
	ds_bpermute_b32 v83, v193, v82
	s_waitcnt lgkmcnt(0)
	v_add_f32_e32 v82, v82, v83
	ds_bpermute_b32 v83, v194, v82
	s_waitcnt lgkmcnt(0)
	v_add_f32_e32 v82, v82, v83
	v_fmamk_f32 v82, v82, 0x39800000, v179
	v_mul_f32_e32 v83, 0x4f800000, v82
	v_cmp_gt_f32_e32 vcc, s48, v82
	s_nop 1
	v_cndmask_b32_e32 v82, v82, v83, vcc
	v_sqrt_f32_e32 v83, v82
	s_nop 0
	v_add_u32_e32 v104, -1, v83
	v_fma_f32 v105, -v104, v83, v82
	v_cmp_ge_f32_e64 s[0:1], 0, v105
	v_add_u32_e32 v105, 1, v83
	s_nop 0
	v_cndmask_b32_e64 v104, v83, v104, s[0:1]
	v_fma_f32 v83, -v105, v83, v82
	v_cmp_lt_f32_e64 s[0:1], 0, v83
	s_nop 1
	v_cndmask_b32_e64 v83, v104, v105, s[0:1]
	v_mul_f32_e32 v104, 0x37800000, v83
	v_cndmask_b32_e32 v83, v83, v104, vcc
	v_cmp_class_f32_e32 vcc, v82, v237
	s_nop 1
	v_cndmask_b32_e32 v82, v83, v82, vcc
	v_div_scale_f32 v83, s[0:1], v82, v82, 1.0
	v_rcp_f32_e32 v104, v83
	s_lshl_b64 s[0:1], s[24:25], 12
	s_and_b64 s[24:25], s[26:27], exec
	s_cselect_b32 s2, 0, s2
	v_fma_f32 v105, -v83, v104, 1.0
	v_fmac_f32_e32 v104, v105, v104
	v_div_scale_f32 v105, vcc, 1.0, v82, 1.0
	v_mul_f32_e32 v110, v105, v104
	v_fma_f32 v111, -v83, v110, v105
	v_fmac_f32_e32 v110, v111, v104
	v_fma_f32 v83, -v83, v110, v105
	v_div_fmas_f32 v83, v83, v104, v110
	v_div_fixup_f32 v82, v83, v82, 1.0
	v_add_u32_e32 v83, s2, v236
	ds_read_b128 v[124:127], v83 offset:49152
	ds_read_b128 v[186:189], v83 offset:50176
	ds_read_b128 v[182:185], v83 offset:32768
	ds_read_b128 v[190:193], v83 offset:33792
	v_pk_mul_f32 v[84:85], v[84:85], v[82:83] op_sel_hi:[1,0]
	s_waitcnt lgkmcnt(3)
	v_pk_add_f32 v[110:111], v[124:125], 1.0 op_sel_hi:[1,0]
	v_pk_mul_f32 v[78:79], v[78:79], v[82:83] op_sel_hi:[1,0]
	s_waitcnt lgkmcnt(1)
	v_pk_fma_f32 v[84:85], v[110:111], v[84:85], v[182:183]
	v_mov_b32_e32 v110, v181
	v_cvt_pk_fp8_f32 v110, v84, v85
	v_pk_mul_f32 v[84:85], v[86:87], v[82:83] op_sel_hi:[1,0]
	v_pk_add_f32 v[86:87], v[126:127], 1.0 op_sel_hi:[1,0]
	v_mov_b32_e32 v111, v181
	v_pk_fma_f32 v[84:85], v[86:87], v[84:85], v[184:185]
	v_pk_mul_f32 v[86:87], v[94:95], v[82:83] op_sel_hi:[1,0]
	v_cvt_pk_fp8_f32 v110, v84, v85 op_sel:[0,0,1]
	v_pk_mul_f32 v[84:85], v[92:93], v[82:83] op_sel_hi:[1,0]
	v_pk_add_f32 v[92:93], v[186:187], 1.0 op_sel_hi:[1,0]
	ds_read_b128 v[124:127], v83 offset:52224
	s_waitcnt lgkmcnt(1)
	v_pk_fma_f32 v[84:85], v[92:93], v[84:85], v[190:191]
	ds_read_b128 v[182:185], v83 offset:35840
	v_cvt_pk_fp8_f32 v111, v84, v85
	v_pk_add_f32 v[84:85], v[188:189], 1.0 op_sel_hi:[1,0]
	v_pk_mul_f32 v[74:75], v[74:75], v[82:83] op_sel_hi:[1,0]
	v_pk_fma_f32 v[92:93], v[84:85], v[86:87], v[192:193]
	ds_read_b128 v[84:87], v83 offset:51200
	v_cvt_pk_fp8_f32 v111, v92, v93 op_sel:[0,0,1]
	ds_read_b128 v[92:95], v83 offset:34816
	v_lshl_add_u64 v[104:105], v[176:177], 0, s[0:1]
	v_pk_mul_f32 v[70:71], v[70:71], v[82:83] op_sel_hi:[1,0]
	s_waitcnt lgkmcnt(1)
	v_pk_add_f32 v[84:85], v[84:85], 1.0 op_sel_hi:[1,0]
	v_pk_mul_f32 v[88:89], v[88:89], v[82:83] op_sel_hi:[1,0]
	s_waitcnt lgkmcnt(0)
	v_pk_fma_f32 v[78:79], v[84:85], v[78:79], v[92:93]
	v_mov_b32_e32 v84, v181
	v_cvt_pk_fp8_f32 v84, v78, v79
	v_pk_mul_f32 v[78:79], v[80:81], v[82:83] op_sel_hi:[1,0]
	v_pk_add_f32 v[80:81], v[86:87], 1.0 op_sel_hi:[1,0]
	v_pk_mul_f32 v[66:67], v[66:67], v[82:83] op_sel_hi:[1,0]
	v_pk_fma_f32 v[78:79], v[80:81], v[78:79], v[94:95]
	s_add_u32 s14, s14, s34
	v_cvt_pk_fp8_f32 v84, v78, v79 op_sel:[0,0,1]
	v_pk_add_f32 v[78:79], v[124:125], 1.0 op_sel_hi:[1,0]
	s_addc_u32 s15, s15, s35
	v_pk_fma_f32 v[74:75], v[78:79], v[74:75], v[182:183]
	v_mov_b32_e32 v78, v181
	v_cvt_pk_fp8_f32 v78, v74, v75
	v_pk_mul_f32 v[74:75], v[76:77], v[82:83] op_sel_hi:[1,0]
	v_pk_add_f32 v[76:77], v[126:127], 1.0 op_sel_hi:[1,0]
	s_add_u32 s4, s4, s6
	v_pk_fma_f32 v[74:75], v[76:77], v[74:75], v[184:185]
	s_addc_u32 s5, s5, s7
	v_cvt_pk_fp8_f32 v78, v74, v75 op_sel:[0,0,1]
	global_store_dword v[104:105], v110, off
	global_store_dword v[104:105], v111, off offset:256
	global_store_dword v[104:105], v84, off offset:512
	global_store_dword v[104:105], v78, off offset:768
	ds_read_b128 v[74:77], v83 offset:53248
	ds_read_b128 v[78:81], v83 offset:36864
	ds_read_b128 v[84:87], v83 offset:54272
	ds_read_b128 v[92:95], v83 offset:37888
	v_mov_b32_e32 v110, v181
	s_waitcnt lgkmcnt(3)
	v_pk_add_f32 v[74:75], v[74:75], 1.0 op_sel_hi:[1,0]
	s_add_i32 s19, s19, s44
	s_waitcnt lgkmcnt(2)
	v_pk_fma_f32 v[70:71], v[74:75], v[70:71], v[78:79]
	s_waitcnt lgkmcnt(1)
	v_pk_add_f32 v[74:75], v[84:85], 1.0 op_sel_hi:[1,0]
	v_cvt_pk_fp8_f32 v110, v70, v71
	v_pk_mul_f32 v[70:71], v[72:73], v[82:83] op_sel_hi:[1,0]
	v_pk_add_f32 v[72:73], v[76:77], 1.0 op_sel_hi:[1,0]
	s_andn2_b64 vcc, exec, s[38:39]
	v_pk_fma_f32 v[70:71], v[72:73], v[70:71], v[80:81]
	v_pk_mul_f32 v[72:73], v[114:115], v[82:83] op_sel_hi:[1,0]
	v_cvt_pk_fp8_f32 v110, v70, v71 op_sel:[0,0,1]
	v_pk_mul_f32 v[70:71], v[112:113], v[82:83] op_sel_hi:[1,0]
	ds_read_b128 v[78:81], v83 offset:56320
	s_waitcnt lgkmcnt(1)
	v_pk_fma_f32 v[70:71], v[74:75], v[70:71], v[92:93]
	v_mov_b32_e32 v92, v181
	v_cvt_pk_fp8_f32 v92, v70, v71
	v_pk_add_f32 v[70:71], v[86:87], 1.0 op_sel_hi:[1,0]
	ds_read_b128 v[84:87], v83 offset:39936
	v_pk_fma_f32 v[74:75], v[70:71], v[72:73], v[94:95]
	ds_read_b128 v[70:73], v83 offset:55296
	v_cvt_pk_fp8_f32 v92, v74, v75 op_sel:[0,0,1]
	ds_read_b128 v[74:77], v83 offset:38912
	s_mov_b32 s24, s36
	s_waitcnt lgkmcnt(1)
	v_pk_add_f32 v[70:71], v[70:71], 1.0 op_sel_hi:[1,0]
	v_pk_add_f32 v[72:73], v[72:73], 1.0 op_sel_hi:[1,0]
	s_waitcnt lgkmcnt(0)
	v_pk_fma_f32 v[70:71], v[88:89], v[70:71], v[74:75]
	v_mov_b32_e32 v74, v181
	v_cvt_pk_fp8_f32 v74, v70, v71
	v_pk_mul_f32 v[70:71], v[90:91], v[82:83] op_sel_hi:[1,0]
	v_mov_b32_e32 v75, v181
	v_pk_fma_f32 v[70:71], v[70:71], v[72:73], v[76:77]
	v_pk_add_f32 v[72:73], v[78:79], 1.0 op_sel_hi:[1,0]
	v_cvt_pk_fp8_f32 v74, v70, v71 op_sel:[0,0,1]
	v_pk_mul_f32 v[70:71], v[96:97], v[82:83] op_sel_hi:[1,0]
	v_mov_b32_e32 v88, v181
	v_pk_fma_f32 v[70:71], v[70:71], v[72:73], v[84:85]
	v_pk_add_f32 v[72:73], v[80:81], 1.0 op_sel_hi:[1,0]
	v_cvt_pk_fp8_f32 v75, v70, v71
	v_pk_mul_f32 v[70:71], v[98:99], v[82:83] op_sel_hi:[1,0]
	v_mov_b32_e32 v89, v181
	v_pk_fma_f32 v[70:71], v[70:71], v[72:73], v[86:87]
	s_nop 0
	v_cvt_pk_fp8_f32 v75, v70, v71 op_sel:[0,0,1]
	global_store_dword v[104:105], v110, off offset:1024
	global_store_dword v[104:105], v92, off offset:1280
	global_store_dword v[104:105], v74, off offset:1536
	global_store_dword v[104:105], v75, off offset:1792
	ds_read_b128 v[70:73], v83 offset:57344
	ds_read_b128 v[74:77], v83 offset:40960
	ds_read_b128 v[78:81], v83 offset:58368
	ds_read_b128 v[84:87], v83 offset:41984
	s_waitcnt lgkmcnt(3)
	v_pk_add_f32 v[70:71], v[70:71], 1.0 op_sel_hi:[1,0]
	s_waitcnt lgkmcnt(2)
	v_pk_fma_f32 v[66:67], v[66:67], v[70:71], v[74:75]
	s_waitcnt lgkmcnt(1)
	v_pk_add_f32 v[70:71], v[78:79], 1.0 op_sel_hi:[1,0]
	v_cvt_pk_fp8_f32 v88, v66, v67
	v_pk_mul_f32 v[66:67], v[68:69], v[82:83] op_sel_hi:[1,0]
	v_pk_add_f32 v[68:69], v[72:73], 1.0 op_sel_hi:[1,0]
	s_nop 0
	v_pk_fma_f32 v[66:67], v[66:67], v[68:69], v[76:77]
	v_pk_mul_f32 v[68:69], v[130:131], v[82:83] op_sel_hi:[1,0]
	v_cvt_pk_fp8_f32 v88, v66, v67 op_sel:[0,0,1]
	v_pk_mul_f32 v[66:67], v[128:129], v[82:83] op_sel_hi:[1,0]
	ds_read_b128 v[74:77], v83 offset:60416
	s_waitcnt lgkmcnt(1)
	v_pk_fma_f32 v[66:67], v[66:67], v[70:71], v[84:85]
	v_pk_mul_f32 v[84:85], v[106:107], v[82:83] op_sel_hi:[1,0]
	v_cvt_pk_fp8_f32 v89, v66, v67
	v_pk_add_f32 v[66:67], v[80:81], 1.0 op_sel_hi:[1,0]
	ds_read_b128 v[78:81], v83 offset:44032
	v_pk_fma_f32 v[70:71], v[68:69], v[66:67], v[86:87]
	ds_read_b128 v[66:69], v83 offset:59392
	v_cvt_pk_fp8_f32 v89, v70, v71 op_sel:[0,0,1]
	ds_read_b128 v[70:73], v83 offset:43008
	v_mov_b32_e32 v86, v181
	v_mov_b32_e32 v87, v181
	s_waitcnt lgkmcnt(1)
	v_pk_add_f32 v[66:67], v[66:67], 1.0 op_sel_hi:[1,0]
	v_pk_add_f32 v[68:69], v[68:69], 1.0 op_sel_hi:[1,0]
	s_waitcnt lgkmcnt(0)
	v_pk_fma_f32 v[66:67], v[84:85], v[66:67], v[70:71]
	v_mov_b32_e32 v70, v181
	v_cvt_pk_fp8_f32 v70, v66, v67
	v_pk_mul_f32 v[66:67], v[108:109], v[82:83] op_sel_hi:[1,0]
	v_mov_b32_e32 v71, v181
	v_pk_fma_f32 v[66:67], v[66:67], v[68:69], v[72:73]
	v_pk_add_f32 v[68:69], v[74:75], 1.0 op_sel_hi:[1,0]
	v_cvt_pk_fp8_f32 v70, v66, v67 op_sel:[0,0,1]
	v_pk_mul_f32 v[66:67], v[100:101], v[82:83] op_sel_hi:[1,0]
	v_pk_mul_f32 v[84:85], v[132:133], v[82:83] op_sel_hi:[1,0]
	v_pk_fma_f32 v[66:67], v[66:67], v[68:69], v[78:79]
	v_pk_add_f32 v[68:69], v[76:77], 1.0 op_sel_hi:[1,0]
	v_cvt_pk_fp8_f32 v71, v66, v67
	v_pk_mul_f32 v[66:67], v[102:103], v[82:83] op_sel_hi:[1,0]
	s_nop 0
	v_pk_fma_f32 v[66:67], v[66:67], v[68:69], v[80:81]
	s_nop 0
	v_cvt_pk_fp8_f32 v71, v66, v67 op_sel:[0,0,1]
	global_store_dword v[104:105], v88, off offset:2048
	global_store_dword v[104:105], v89, off offset:2304
	global_store_dword v[104:105], v70, off offset:2560
	global_store_dword v[104:105], v71, off offset:2816
	ds_read_b128 v[66:69], v83 offset:61440
	ds_read_b128 v[70:73], v83 offset:45056
	ds_read_b128 v[74:77], v83 offset:62464
	ds_read_b128 v[78:81], v83 offset:46080
	s_waitcnt lgkmcnt(3)
	v_pk_add_f32 v[66:67], v[66:67], 1.0 op_sel_hi:[1,0]
	s_waitcnt lgkmcnt(2)
	v_pk_fma_f32 v[66:67], v[84:85], v[66:67], v[70:71]
	v_pk_add_f32 v[68:69], v[68:69], 1.0 op_sel_hi:[1,0]
	v_cvt_pk_fp8_f32 v86, v66, v67
	v_pk_mul_f32 v[66:67], v[134:135], v[82:83] op_sel_hi:[1,0]
	s_waitcnt lgkmcnt(1)
	v_pk_add_f32 v[70:71], v[74:75], 1.0 op_sel_hi:[1,0]
	v_pk_fma_f32 v[66:67], v[66:67], v[68:69], v[72:73]
	v_pk_mul_f32 v[68:69], v[138:139], v[82:83] op_sel_hi:[1,0]
	v_cvt_pk_fp8_f32 v86, v66, v67 op_sel:[0,0,1]
	v_pk_mul_f32 v[66:67], v[136:137], v[82:83] op_sel_hi:[1,0]
	v_pk_mul_f32 v[84:85], v[120:121], v[82:83] op_sel_hi:[1,0]
	s_waitcnt lgkmcnt(0)
	v_pk_fma_f32 v[66:67], v[66:67], v[70:71], v[78:79]
	s_nop 0
	v_cvt_pk_fp8_f32 v87, v66, v67
	v_pk_add_f32 v[66:67], v[76:77], 1.0 op_sel_hi:[1,0]
	ds_read_b128 v[74:77], v83 offset:64512
	v_pk_fma_f32 v[70:71], v[68:69], v[66:67], v[80:81]
	ds_read_b128 v[66:69], v83 offset:63488
	v_cvt_pk_fp8_f32 v87, v70, v71 op_sel:[0,0,1]
	ds_read_b128 v[70:73], v83 offset:47104
	ds_read_b128 v[78:81], v83 offset:48128
	s_waitcnt lgkmcnt(2)
	v_pk_add_f32 v[66:67], v[66:67], 1.0 op_sel_hi:[1,0]
	v_pk_add_f32 v[68:69], v[68:69], 1.0 op_sel_hi:[1,0]
	s_waitcnt lgkmcnt(1)
	v_pk_fma_f32 v[66:67], v[84:85], v[66:67], v[70:71]
	v_mov_b32_e32 v70, v181
	v_cvt_pk_fp8_f32 v70, v66, v67
	v_pk_mul_f32 v[66:67], v[122:123], v[82:83] op_sel_hi:[1,0]
	v_mov_b32_e32 v71, v181
	v_pk_fma_f32 v[66:67], v[66:67], v[68:69], v[72:73]
	v_pk_add_f32 v[68:69], v[74:75], 1.0 op_sel_hi:[1,0]
	v_cvt_pk_fp8_f32 v70, v66, v67 op_sel:[0,0,1]
	v_pk_mul_f32 v[66:67], v[116:117], v[82:83] op_sel_hi:[1,0]
	s_waitcnt lgkmcnt(0)
	v_pk_fma_f32 v[66:67], v[66:67], v[68:69], v[78:79]
	v_pk_add_f32 v[68:69], v[76:77], 1.0 op_sel_hi:[1,0]
	v_cvt_pk_fp8_f32 v71, v66, v67
	v_pk_mul_f32 v[66:67], v[118:119], v[82:83] op_sel_hi:[1,0]
	s_nop 0
	v_pk_fma_f32 v[66:67], v[66:67], v[68:69], v[80:81]
	s_nop 0
	v_cvt_pk_fp8_f32 v71, v66, v67 op_sel:[0,0,1]
	global_store_dword v[104:105], v86, off offset:3072
	global_store_dword v[104:105], v87, off offset:3328
	global_store_dword v[104:105], v70, off offset:3584
	global_store_dword v[104:105], v71, off offset:3840
	s_cbranch_vccz .LBB0_883

.LBB0_1111:
	v_add_f32_e32 v164, v126, v127
	v_add_f32_e32 v165, v128, v129
	v_add_f32_e32 v164, v164, v165
	v_and_b32_e32 v165, 64, v233
	v_add_u32_e32 v165, 64, v165
	v_xor_b32_e32 v166, 1, v233
	v_cmp_lt_i32_e32 vcc, v166, v165
	v_add_f32_e32 v164, v234, v164
	s_add_u32 s6, s60, s34
	v_cndmask_b32_e32 v166, v233, v166, vcc
	v_lshlrev_b32_e32 v182, 2, v166
	ds_bpermute_b32 v166, v182, v164
	s_addc_u32 s7, s61, s5
	s_and_b64 s[0:1], s[0:1], exec
	s_cselect_b32 s0, 0, 0x8000000
	s_cselect_b32 s9, s61, 0
	s_waitcnt lgkmcnt(0)
	v_add_f32_e32 v164, v164, v166
	v_xor_b32_e32 v166, 2, v233
	v_cmp_lt_i32_e32 vcc, v166, v165
	s_cselect_b32 s8, s60, s2
	s_add_u32 s2, s30, s0
	v_cndmask_b32_e32 v166, v233, v166, vcc
	v_lshlrev_b32_e32 v183, 2, v166
	ds_bpermute_b32 v166, v183, v164
	s_addc_u32 s10, s31, 0
	s_mov_b64 s[60:61], s[6:7]
	s_waitcnt lgkmcnt(0)
	v_add_f32_e32 v164, v164, v166
	v_xor_b32_e32 v166, 4, v233
	v_cmp_lt_i32_e32 vcc, v166, v165
	s_nop 1
	v_cndmask_b32_e32 v166, v233, v166, vcc
	v_lshlrev_b32_e32 v184, 2, v166
	ds_bpermute_b32 v166, v184, v164
	s_waitcnt lgkmcnt(0)
	v_add_f32_e32 v164, v164, v166
	v_xor_b32_e32 v166, 8, v233
	v_cmp_lt_i32_e32 vcc, v166, v165
	s_nop 1
	v_cndmask_b32_e32 v166, v233, v166, vcc
	v_lshlrev_b32_e32 v185, 2, v166
	ds_bpermute_b32 v166, v185, v164
	s_waitcnt lgkmcnt(0)
	v_add_f32_e32 v164, v164, v166
	v_xor_b32_e32 v166, 16, v233
	v_cmp_lt_i32_e32 vcc, v166, v165
	s_nop 1
	v_cndmask_b32_e32 v166, v233, v166, vcc
	v_lshlrev_b32_e32 v186, 2, v166
	ds_bpermute_b32 v166, v186, v164
	s_waitcnt lgkmcnt(0)
	v_add_f32_e32 v164, v164, v166
	v_xor_b32_e32 v166, 32, v233
	v_cmp_lt_i32_e32 vcc, v166, v165
	s_nop 1
	v_cndmask_b32_e32 v165, v233, v166, vcc
	v_lshlrev_b32_e32 v187, 2, v165
	ds_bpermute_b32 v165, v187, v164
	s_waitcnt lgkmcnt(0)
	v_add_f32_e32 v188, v164, v165
	v_fmamk_f32 v179, v188, 0xb9800000, v67
	v_fmamk_f32 v178, v188, 0xb9800000, v66
	v_fmamk_f32 v69, v188, 0xb9800000, v69
	v_fmac_f32_e32 v68, 0xb9800000, v188
	v_pk_mul_f32 v[66:67], v[68:69], v[68:69]
	v_pk_mul_f32 v[164:165], v[178:179], v[178:179]
	v_fmamk_f32 v175, v188, 0xb9800000, v71
	v_pk_mov_b32 v[166:167], v[164:165], v[66:67] op_sel:[1,0]
	v_mov_b32_e32 v165, v67
	v_pk_add_f32 v[66:67], v[166:167], v[164:165]
	v_fmamk_f32 v174, v188, 0xb9800000, v70
	v_fmamk_f32 v73, v188, 0xb9800000, v73
	v_fmac_f32_e32 v72, 0xb9800000, v188
	v_pk_add_f32 v[66:67], v[66:67], v[66:67] op_sel_hi:[0,1]
	v_pk_mul_f32 v[70:71], v[72:73], v[72:73]
	v_pk_mul_f32 v[164:165], v[174:175], v[174:175]
	v_fmamk_f32 v176, v188, 0xb9800000, v78
	v_pk_mov_b32 v[166:167], v[164:165], v[70:71] op_sel:[1,0]
	v_mov_b32_e32 v165, v71
	v_fmamk_f32 v177, v188, 0xb9800000, v79
	v_fmac_f32_e32 v80, 0xb9800000, v188
	v_mul_f32_e32 v66, v176, v176
	v_pk_add_f32 v[70:71], v[166:167], v[164:165]
	v_fmamk_f32 v81, v188, 0xb9800000, v81
	v_pk_fma_f32 v[78:79], v[176:177], v[176:177], v[66:67] op_sel_hi:[1,1,0]
	v_mul_f32_e32 v66, v80, v80
	v_pk_add_f32 v[70:71], v[70:71], v[70:71] op_sel_hi:[0,1]
	v_pk_fma_f32 v[164:165], v[80:81], v[80:81], v[66:67] op_sel_hi:[1,1,0]
	v_fmamk_f32 v171, v188, 0xb9800000, v85
	v_fmamk_f32 v170, v188, 0xb9800000, v84
	v_fmamk_f32 v83, v188, 0xb9800000, v83
	v_fmac_f32_e32 v82, 0xb9800000, v188
	v_mul_f32_e32 v78, v82, v82
	v_mul_f32_e32 v164, v83, v83
	v_mul_f32_e32 v66, v170, v170
	v_mul_f32_e32 v70, v171, v171
	v_pk_add_f32 v[78:79], v[78:79], v[164:165]
	v_pk_add_f32 v[66:67], v[66:67], v[70:71]
	v_fmamk_f32 v173, v188, 0xb9800000, v87
	v_pk_add_f32 v[66:67], v[78:79], v[66:67]
	v_fmamk_f32 v172, v188, 0xb9800000, v86
	v_fmamk_f32 v89, v188, 0xb9800000, v89
	v_fmac_f32_e32 v88, 0xb9800000, v188
	v_pk_add_f32 v[66:67], v[66:67], v[66:67] op_sel_hi:[0,1]
	v_pk_mul_f32 v[70:71], v[88:89], v[88:89]
	v_pk_mul_f32 v[78:79], v[172:173], v[172:173]
	v_fmamk_f32 v168, v188, 0xb9800000, v74
	v_pk_mov_b32 v[84:85], v[78:79], v[70:71] op_sel:[1,0]
	v_mov_b32_e32 v79, v71
	v_fmamk_f32 v169, v188, 0xb9800000, v75
	v_fmac_f32_e32 v76, 0xb9800000, v188
	v_mul_f32_e32 v66, v168, v168
	v_pk_add_f32 v[70:71], v[84:85], v[78:79]
	v_fmamk_f32 v77, v188, 0xb9800000, v77
	v_pk_fma_f32 v[74:75], v[168:169], v[168:169], v[66:67] op_sel_hi:[1,1,0]
	v_mul_f32_e32 v66, v76, v76
	v_pk_add_f32 v[70:71], v[70:71], v[70:71] op_sel_hi:[0,1]
	v_pk_fma_f32 v[78:79], v[76:77], v[76:77], v[66:67] op_sel_hi:[1,1,0]
	v_fmamk_f32 v165, v188, 0xb9800000, v93
	v_fmamk_f32 v164, v188, 0xb9800000, v92
	v_fmamk_f32 v91, v188, 0xb9800000, v91
	v_fmac_f32_e32 v90, 0xb9800000, v188
	v_mul_f32_e32 v74, v90, v90
	v_mul_f32_e32 v78, v91, v91
	v_mul_f32_e32 v70, v164, v164
	v_mul_f32_e32 v66, v165, v165
	v_pk_add_f32 v[74:75], v[74:75], v[78:79]
	v_pk_add_f32 v[66:67], v[70:71], v[66:67]
	v_fmamk_f32 v167, v188, 0xb9800000, v95
	v_pk_add_f32 v[66:67], v[74:75], v[66:67]
	v_fmamk_f32 v166, v188, 0xb9800000, v94
	v_fmamk_f32 v97, v188, 0xb9800000, v97
	v_fmac_f32_e32 v96, 0xb9800000, v188
	v_pk_add_f32 v[66:67], v[66:67], v[66:67] op_sel_hi:[0,1]
	v_pk_mul_f32 v[70:71], v[96:97], v[96:97]
	v_pk_mul_f32 v[74:75], v[166:167], v[166:167]
	v_fmamk_f32 v94, v188, 0xb9800000, v98
	v_pk_mov_b32 v[78:79], v[74:75], v[70:71] op_sel:[1,0]
	v_mov_b32_e32 v75, v71
	v_fmamk_f32 v95, v188, 0xb9800000, v99
	v_fmac_f32_e32 v100, 0xb9800000, v188
	v_mul_f32_e32 v66, v94, v94
	v_pk_add_f32 v[70:71], v[78:79], v[74:75]
	v_fmamk_f32 v101, v188, 0xb9800000, v101
	v_pk_fma_f32 v[74:75], v[94:95], v[94:95], v[66:67] op_sel_hi:[1,1,0]
	v_mul_f32_e32 v66, v100, v100
	v_pk_add_f32 v[70:71], v[70:71], v[70:71] op_sel_hi:[0,1]
	v_pk_fma_f32 v[78:79], v[100:101], v[100:101], v[66:67] op_sel_hi:[1,1,0]
	v_fmamk_f32 v85, v188, 0xb9800000, v105
	v_fmamk_f32 v84, v188, 0xb9800000, v104
	v_fmamk_f32 v103, v188, 0xb9800000, v103
	v_fmac_f32_e32 v102, 0xb9800000, v188
	v_mul_f32_e32 v74, v102, v102
	v_mul_f32_e32 v78, v103, v103
	v_mul_f32_e32 v70, v84, v84
	v_mul_f32_e32 v66, v85, v85
	v_pk_add_f32 v[74:75], v[74:75], v[78:79]
	v_pk_add_f32 v[66:67], v[70:71], v[66:67]
	v_fmamk_f32 v93, v188, 0xb9800000, v107
	v_pk_add_f32 v[66:67], v[74:75], v[66:67]
	v_fmamk_f32 v92, v188, 0xb9800000, v106
	v_fmamk_f32 v109, v188, 0xb9800000, v109
	v_fmac_f32_e32 v108, 0xb9800000, v188
	v_pk_add_f32 v[66:67], v[66:67], v[66:67] op_sel_hi:[0,1]
	v_pk_mul_f32 v[70:71], v[108:109], v[108:109]
	v_pk_mul_f32 v[74:75], v[92:93], v[92:93]
	v_fmamk_f32 v86, v188, 0xb9800000, v110
	v_pk_mov_b32 v[78:79], v[74:75], v[70:71] op_sel:[1,0]
	v_mov_b32_e32 v75, v71
	v_fmamk_f32 v87, v188, 0xb9800000, v111
	v_fmac_f32_e32 v112, 0xb9800000, v188
	v_mul_f32_e32 v66, v86, v86
	v_pk_add_f32 v[70:71], v[78:79], v[74:75]
	v_fmamk_f32 v113, v188, 0xb9800000, v113
	v_pk_fma_f32 v[74:75], v[86:87], v[86:87], v[66:67] op_sel_hi:[1,1,0]
	v_mul_f32_e32 v66, v112, v112
	v_pk_add_f32 v[70:71], v[70:71], v[70:71] op_sel_hi:[0,1]
	v_pk_fma_f32 v[98:99], v[112:113], v[112:113], v[66:67] op_sel_hi:[1,1,0]
	v_fmamk_f32 v79, v188, 0xb9800000, v117
	v_fmamk_f32 v78, v188, 0xb9800000, v116
	v_fmamk_f32 v115, v188, 0xb9800000, v115
	v_fmac_f32_e32 v114, 0xb9800000, v188
	v_mul_f32_e32 v74, v114, v114
	v_mul_f32_e32 v98, v115, v115
	v_mul_f32_e32 v70, v78, v78
	v_mul_f32_e32 v66, v79, v79
	v_pk_add_f32 v[74:75], v[74:75], v[98:99]
	v_pk_add_f32 v[66:67], v[70:71], v[66:67]
	v_fmamk_f32 v71, v188, 0xb9800000, v119
	v_pk_add_f32 v[66:67], v[74:75], v[66:67]
	v_fmamk_f32 v70, v188, 0xb9800000, v118
	v_fmamk_f32 v121, v188, 0xb9800000, v121
	v_fmac_f32_e32 v120, 0xb9800000, v188
	v_pk_add_f32 v[98:99], v[66:67], v[66:67] op_sel_hi:[0,1]
	v_pk_mul_f32 v[66:67], v[120:121], v[120:121]
	v_pk_mul_f32 v[74:75], v[70:71], v[70:71]
	v_fmac_f32_e32 v124, 0xb9800000, v188
	v_pk_mov_b32 v[104:105], v[74:75], v[66:67] op_sel:[1,0]
	v_mov_b32_e32 v75, v67
	v_pk_add_f32 v[66:67], v[104:105], v[74:75]
	v_fmamk_f32 v74, v188, 0xb9800000, v122
	v_pk_add_f32 v[104:105], v[66:67], v[66:67] op_sel_hi:[0,1]
	v_fmamk_f32 v75, v188, 0xb9800000, v123
	v_mul_f32_e32 v66, v74, v74
	v_fmamk_f32 v125, v188, 0xb9800000, v125
	v_pk_fma_f32 v[106:107], v[74:75], v[74:75], v[66:67] op_sel_hi:[1,1,0]
	v_mul_f32_e32 v66, v124, v124
	v_pk_fma_f32 v[110:111], v[124:125], v[124:125], v[66:67] op_sel_hi:[1,1,0]
	v_fmamk_f32 v67, v188, 0xb9800000, v129
	v_fmamk_f32 v66, v188, 0xb9800000, v128
	v_fmamk_f32 v127, v188, 0xb9800000, v127
	v_fmac_f32_e32 v126, 0xb9800000, v188
	v_mul_f32_e32 v106, v126, v126
	v_mul_f32_e32 v110, v127, v127
	v_mul_f32_e32 v104, v66, v66
	v_mul_f32_e32 v98, v67, v67
	v_pk_add_f32 v[106:107], v[106:107], v[110:111]
	v_pk_add_f32 v[98:99], v[104:105], v[98:99]
	s_nop 0
	v_pk_add_f32 v[98:99], v[106:107], v[98:99]
	s_nop 0
	v_add_f32_e32 v98, v98, v99
	ds_bpermute_b32 v99, v182, v98
	s_waitcnt lgkmcnt(0)
	v_add_f32_e32 v98, v98, v99
	ds_bpermute_b32 v99, v183, v98
	s_waitcnt lgkmcnt(0)
	v_add_f32_e32 v98, v98, v99
	ds_bpermute_b32 v99, v184, v98
	s_waitcnt lgkmcnt(0)
	v_add_f32_e32 v98, v98, v99
	ds_bpermute_b32 v99, v185, v98
	ds_read_b128 v[116:119], v230
	ds_read_b128 v[182:185], v230 offset:16384
	s_waitcnt lgkmcnt(2)
	v_add_f32_e32 v98, v98, v99
	ds_bpermute_b32 v99, v186, v98
	s_waitcnt lgkmcnt(0)
	v_add_f32_e32 v98, v98, v99
	ds_bpermute_b32 v99, v187, v98
	ds_read_b128 v[186:189], v230 offset:17408
	ds_read_b128 v[190:193], v230 offset:1024
	s_waitcnt lgkmcnt(2)
	v_add_f32_e32 v98, v98, v99
	v_fmamk_f32 v98, v98, 0x39800000, v231
	v_mul_f32_e32 v99, 0x4f800000, v98
	v_cmp_gt_f32_e32 vcc, s17, v98
	s_nop 1
	v_cndmask_b32_e32 v98, v98, v99, vcc
	v_sqrt_f32_e32 v99, v98
	s_nop 0
	v_add_u32_e32 v104, -1, v99
	v_fma_f32 v105, -v104, v99, v98
	v_cmp_ge_f32_e64 s[0:1], 0, v105
	v_add_u32_e32 v105, 1, v99
	s_nop 0
	v_cndmask_b32_e64 v104, v99, v104, s[0:1]
	v_fma_f32 v99, -v105, v99, v98
	v_cmp_lt_f32_e64 s[0:1], 0, v99
	s_nop 1
	v_cndmask_b32_e64 v99, v104, v105, s[0:1]
	v_mul_f32_e32 v104, 0x37800000, v99
	v_cndmask_b32_e32 v99, v99, v104, vcc
	v_cmp_class_f32_e32 vcc, v98, v232
	s_nop 1
	v_cndmask_b32_e32 v98, v99, v98, vcc
	v_div_scale_f32 v99, s[0:1], v98, v98, 1.0
	v_rcp_f32_e32 v104, v99
	s_lshl_b64 s[0:1], s[8:9], 14
	s_add_u32 s0, s2, s0
	s_addc_u32 s1, s10, s1
	v_fma_f32 v105, -v99, v104, 1.0
	v_fmac_f32_e32 v104, v105, v104
	v_div_scale_f32 v105, vcc, 1.0, v98, 1.0
	v_mul_f32_e32 v106, v105, v104
	v_fma_f32 v107, -v99, v106, v105
	v_fmac_f32_e32 v106, v107, v104
	v_fma_f32 v99, -v99, v106, v105
	v_div_fmas_f32 v99, v99, v104, v106
	v_div_fixup_f32 v98, v99, v98, 1.0
	v_pk_mul_f32 v[106:107], v[178:179], v[98:99] op_sel_hi:[1,0]
	v_pk_mul_f32 v[68:69], v[68:69], v[98:99] op_sel_hi:[1,0]
	v_pk_fma_f32 v[116:117], v[116:117], v[106:107], v[182:183]
	v_pk_fma_f32 v[118:119], v[118:119], v[68:69], v[184:185]
	v_pk_mul_f32 v[68:69], v[174:175], v[98:99] op_sel_hi:[1,0]
	v_pk_mul_f32 v[72:73], v[72:73], v[98:99] op_sel_hi:[1,0]
	global_store_dwordx4 v180, v[116:119], s[0:1] sc1 nt
	v_lshl_add_u64 v[104:105], s[0:1], 0, v[180:181]
	v_pk_mul_f32 v[76:77], v[76:77], v[98:99] op_sel_hi:[1,0]
	s_waitcnt lgkmcnt(0)
	v_pk_fma_f32 v[118:119], v[192:193], v[72:73], v[188:189]
	v_pk_fma_f32 v[116:117], v[190:191], v[68:69], v[186:187]
	global_store_dwordx4 v180, v[116:119], s[0:1] offset:1024 sc1 nt
	ds_read_b128 v[116:119], v230 offset:18432
	ds_read_b128 v[182:185], v230 offset:2048
	v_pk_mul_f32 v[68:69], v[176:177], v[98:99] op_sel_hi:[1,0]
	ds_read_b128 v[174:177], v230 offset:19456
	ds_read_b128 v[186:189], v230 offset:3072
	v_pk_mul_f32 v[72:73], v[80:81], v[98:99] op_sel_hi:[1,0]
	v_pk_mul_f32 v[106:107], v[90:91], v[98:99] op_sel_hi:[1,0]
	s_waitcnt lgkmcnt(2)
	v_pk_fma_f32 v[118:119], v[184:185], v[72:73], v[118:119]
	v_pk_fma_f32 v[116:117], v[182:183], v[68:69], v[116:117]
	v_pk_mul_f32 v[68:69], v[82:83], v[98:99] op_sel_hi:[1,0]
	v_pk_mul_f32 v[72:73], v[170:171], v[98:99] op_sel_hi:[1,0]
	s_waitcnt lgkmcnt(0)
	v_pk_fma_f32 v[80:81], v[186:187], v[68:69], v[174:175]
	v_pk_fma_f32 v[82:83], v[188:189], v[72:73], v[176:177]
	global_store_dwordx4 v180, v[116:119], s[0:1] offset:2048 sc1 nt
	global_store_dwordx4 v180, v[80:83], s[0:1] offset:3072 sc1 nt
	ds_read_b128 v[80:83], v230 offset:4096
	ds_read_b128 v[116:119], v230 offset:20480
	v_pk_mul_f32 v[68:69], v[88:89], v[98:99] op_sel_hi:[1,0]
	v_pk_mul_f32 v[72:73], v[172:173], v[98:99] op_sel_hi:[1,0]
	ds_read_b128 v[170:173], v230 offset:21504
	ds_read_b128 v[174:177], v230 offset:5120
	s_cmpk_lt_i32 s6, 0x2800
	s_waitcnt lgkmcnt(2)
	v_pk_fma_f32 v[82:83], v[82:83], v[68:69], v[118:119]
	v_add_co_u32_e32 v68, vcc, s15, v104
	v_pk_fma_f32 v[80:81], v[80:81], v[72:73], v[116:117]
	s_nop 0
	v_addc_co_u32_e32 v69, vcc, 0, v105, vcc
	v_add_co_u32_e32 v72, vcc, s14, v104
	s_nop 1
	v_addc_co_u32_e32 v73, vcc, 0, v105, vcc
	global_store_dwordx4 v[72:73], v[80:83], off offset:-4096 sc1 nt
	s_nop 1
	v_pk_mul_f32 v[80:81], v[168:169], v[98:99] op_sel_hi:[1,0]
	s_waitcnt lgkmcnt(0)
	v_pk_fma_f32 v[82:83], v[176:177], v[76:77], v[172:173]
	v_pk_fma_f32 v[80:81], v[174:175], v[80:81], v[170:171]
	global_store_dwordx4 v[68:69], v[80:83], off offset:1024 sc1 nt
	ds_read_b128 v[80:83], v230 offset:22528
	ds_read_b128 v[116:119], v230 offset:6144
	ds_read_b128 v[88:91], v230 offset:23552
	ds_read_b128 v[168:171], v230 offset:7168
	v_pk_mul_f32 v[76:77], v[164:165], v[98:99] op_sel_hi:[1,0]
	s_waitcnt lgkmcnt(2)
	v_pk_fma_f32 v[80:81], v[116:117], v[106:107], v[80:81]
	v_pk_fma_f32 v[82:83], v[118:119], v[76:77], v[82:83]
	global_store_dwordx4 v[68:69], v[80:83], off offset:2048 sc1 nt
	v_pk_mul_f32 v[76:77], v[96:97], v[98:99] op_sel_hi:[1,0]
	s_nop 0
	v_pk_mul_f32 v[80:81], v[166:167], v[98:99] op_sel_hi:[1,0]
	s_waitcnt lgkmcnt(0)
	v_pk_fma_f32 v[82:83], v[170:171], v[76:77], v[90:91]
	v_pk_fma_f32 v[80:81], v[168:169], v[80:81], v[88:89]
	global_store_dwordx4 v[68:69], v[80:83], off offset:3072 sc1 nt
	ds_read_b128 v[80:83], v230 offset:8192
	ds_read_b128 v[88:91], v230 offset:24576
	v_pk_mul_f32 v[76:77], v[94:95], v[98:99] op_sel_hi:[1,0]
	ds_read_b128 v[94:97], v230 offset:25600
	ds_read_b128 v[116:119], v230 offset:9216
	v_pk_mul_f32 v[68:69], v[100:101], v[98:99] op_sel_hi:[1,0]
	s_waitcnt lgkmcnt(2)
	v_pk_fma_f32 v[80:81], v[80:81], v[76:77], v[88:89]
	v_pk_fma_f32 v[82:83], v[82:83], v[68:69], v[90:91]
	v_pk_mul_f32 v[68:69], v[84:85], v[98:99] op_sel_hi:[1,0]
	v_pk_mul_f32 v[76:77], v[102:103], v[98:99] op_sel_hi:[1,0]
	global_store_dwordx4 v[72:73], v[80:83], off sc1 nt
	s_waitcnt lgkmcnt(0)
	s_nop 0
	v_pk_fma_f32 v[80:81], v[116:117], v[76:77], v[94:95]
	v_pk_fma_f32 v[82:83], v[118:119], v[68:69], v[96:97]
	global_store_dwordx4 v[72:73], v[80:83], off offset:1024 sc1 nt
	ds_read_b128 v[80:83], v230 offset:26624
	ds_read_b128 v[88:91], v230 offset:10240
	v_pk_mul_f32 v[76:77], v[92:93], v[98:99] op_sel_hi:[1,0]
	ds_read_b128 v[92:95], v230 offset:27648
	ds_read_b128 v[100:103], v230 offset:11264
	v_pk_mul_f32 v[68:69], v[108:109], v[98:99] op_sel_hi:[1,0]
	s_waitcnt lgkmcnt(2)
	v_pk_fma_f32 v[80:81], v[76:77], v[88:89], v[80:81]
	v_pk_fma_f32 v[82:83], v[68:69], v[90:91], v[82:83]
	v_pk_mul_f32 v[68:69], v[112:113], v[98:99] op_sel_hi:[1,0]
	v_pk_mul_f32 v[76:77], v[86:87], v[98:99] op_sel_hi:[1,0]
	global_store_dwordx4 v[72:73], v[80:83], off offset:2048 sc1 nt
	s_waitcnt lgkmcnt(0)
	s_nop 0
	v_pk_fma_f32 v[80:81], v[76:77], v[100:101], v[92:93]
	v_pk_fma_f32 v[82:83], v[68:69], v[102:103], v[94:95]
	global_store_dwordx4 v[72:73], v[80:83], off offset:3072 sc1 nt
	ds_read_b128 v[80:83], v230 offset:12288
	ds_read_b128 v[84:87], v230 offset:28672
	v_pk_mul_f32 v[68:69], v[78:79], v[98:99] op_sel_hi:[1,0]
	ds_read_b128 v[76:79], v230 offset:29696
	ds_read_b128 v[88:91], v230 offset:13312
	v_pk_mul_f32 v[72:73], v[114:115], v[98:99] op_sel_hi:[1,0]
	s_waitcnt lgkmcnt(2)
	v_pk_fma_f32 v[82:83], v[68:69], v[82:83], v[86:87]
	v_pk_fma_f32 v[80:81], v[72:73], v[80:81], v[84:85]
	v_add_co_u32_e32 v84, vcc, s16, v104
	v_pk_mul_f32 v[72:73], v[120:121], v[98:99] op_sel_hi:[1,0]
	v_pk_mul_f32 v[68:69], v[70:71], v[98:99] op_sel_hi:[1,0]
	v_addc_co_u32_e32 v85, vcc, 0, v105, vcc
	s_waitcnt lgkmcnt(0)
	v_pk_fma_f32 v[68:69], v[68:69], v[88:89], v[76:77]
	v_pk_fma_f32 v[70:71], v[72:73], v[90:91], v[78:79]
	global_store_dwordx4 v[84:85], v[80:83], off sc1 nt
	global_store_dwordx4 v[84:85], v[68:71], off offset:1024 sc1 nt
	ds_read_b128 v[68:71], v230 offset:30720
	ds_read_b128 v[76:79], v230 offset:14336
	v_pk_mul_f32 v[88:89], v[74:75], v[98:99] op_sel_hi:[1,0]
	ds_read_b128 v[72:75], v230 offset:31744
	ds_read_b128 v[80:83], v230 offset:15360
	v_pk_mul_f32 v[86:87], v[124:125], v[98:99] op_sel_hi:[1,0]
	s_waitcnt lgkmcnt(2)
	v_pk_fma_f32 v[68:69], v[88:89], v[76:77], v[68:69]
	v_pk_fma_f32 v[70:71], v[86:87], v[78:79], v[70:71]
	global_store_dwordx4 v[84:85], v[68:71], off offset:2048 sc1 nt
	s_nop 1
	v_pk_mul_f32 v[68:69], v[66:67], v[98:99] op_sel_hi:[1,0]
	v_pk_mul_f32 v[66:67], v[126:127], v[98:99] op_sel_hi:[1,0]
	s_waitcnt lgkmcnt(0)
	v_pk_fma_f32 v[68:69], v[68:69], v[82:83], v[74:75]
	v_pk_fma_f32 v[66:67], v[66:67], v[80:81], v[72:73]
	global_store_dwordx4 v[84:85], v[66:69], off offset:3072 sc1 nt
	s_cbranch_scc0 .LBB0_1121
